# FFN up-projection K-loops: first K-tile after an epilogue peeled, its two counted waits exclude the epilogue's 8 stores (vmcnt 16)
# baseline (speedup 1.0000x reference)
.LBB0_58:
	s_mov_b32 s19, 0
	v_readlane_b32 s10, v253, 2
	v_readlane_b32 s11, v253, 3
	s_mov_b64 s[6:7], s[10:11]
	s_mov_b64 s[4:5], s[10:11]
	v_mov_b32_e32 v0, 0x20008
	v_mov_b32_e32 v8, v236
	v_add_u32_e32 v0, 0, v0
	ds_read_b32 v0, v0
	s_waitcnt lgkmcnt(0)
	v_readfirstlane_b32 s0, v0
	s_cmpk_gt_i32 s0, 0x57f
	v_readfirstlane_b32 s14, v8
	s_cbranch_scc1 .LBB0_74
	v_lshlrev_b32_e32 v0, 4, v8
	v_add_u32_e32 v1, 0x2000, v0
	v_ashrrev_i32_e32 v2, 31, v1
	v_lshrrev_b32_e32 v2, 22, v2
	v_add_u32_e32 v2, v1, v2
	v_ashrrev_i32_e32 v9, 10, v2
	v_mul_i32_i24_e32 v2, 0x400, v9
	v_sub_u32_e32 v1, v1, v2
	v_lshrrev_b32_e32 v2, 4, v1
	v_bitop3_b32 v1, v2, v1, 32 bitop3:0x6c
	v_ashrrev_i32_e32 v2, 31, v1
	v_lshrrev_b32_e32 v2, 26, v2
	v_add_u32_e32 v2, v1, v2
	v_lshlrev_b32_e32 v3, 3, v9
	v_ashrrev_i32_e32 v10, 6, v2
	v_and_b32_e32 v3, -16, v3
	v_add_u32_e32 v3, v10, v3
	v_and_b32_e32 v4, 3, v10
	s_mov_b32 s2, 0x1fffe0
	v_lshrrev_b32_e32 v5, 2, v3
	v_lshlrev_b32_e32 v6, 1, v3
	v_and_b32_e32 v2, 0xc0, v2
	v_and_or_b32 v4, v3, s2, v4
	v_and_b32_e32 v5, 4, v5
	v_and_b32_e32 v6, 24, v6
	v_sub_u32_e32 v1, v1, v2
	v_or3_b32 v4, v4, v5, v6
	v_lshlrev_b32_e32 v5, 5, v9
	v_ashrrev_i16_sdwa v1, v237, sext(v1) dst_sel:DWORD dst_unused:UNUSED_PAD src0_sel:DWORD src1_sel:BYTE_0
	v_and_b32_e32 v5, 32, v5
	v_bfe_i32 v11, v1, 0, 16
	v_add_lshl_u32 v1, v5, v11, 1
	v_lshl_add_u32 v128, v4, 11, v1
	v_lshl_add_u32 v130, v3, 11, v1
	v_bfe_i32 v1, v8, 27, 1
	v_lshrrev_b32_e32 v1, 22, v1
	v_add_u32_e32 v1, v0, v1
	v_and_b32_e32 v1, 0xfffffc00, v1
	v_sub_u32_e32 v0, v0, v1
	v_lshrrev_b32_e32 v1, 4, v0
	v_bitop3_b32 v1, v1, v0, 32 bitop3:0x6c
	v_ashrrev_i32_e32 v0, 31, v0
	v_lshrrev_b32_e32 v0, 26, v0
	v_add_u32_e32 v0, v1, v0
	v_ashrrev_i32_e32 v12, 6, v0
	v_ashrrev_i32_e32 v0, 31, v8
	s_load_dwordx2 s[12:13], s[6:7], 0x78
	s_nop 0
	s_load_dwordx2 s[6:7], s[4:5], 0x78
	v_lshrrev_b32_e32 v0, 26, v0
	v_add_u32_e32 v0, v8, v0
	v_ashrrev_i32_e32 v13, 6, v0
	v_lshlrev_b32_e32 v0, 3, v13
	s_waitcnt lgkmcnt(0)
	s_add_u32 s1, s12, 0x3700000
	v_and_b32_e32 v0, -16, v0
	s_addc_u32 s42, s13, 0
	s_ashr_i32 s43, s0, 31
	v_add_u32_e32 v0, v12, v0
	v_and_b32_e32 v2, 3, v12
	v_and_or_b32 v2, v0, s2, v2
	s_lshr_b32 s2, s43, 29
	s_add_i32 s2, s0, s2
	s_ashr_i32 s16, s14, 6
	s_ashr_i32 s4, s2, 3
	s_and_b32 s2, s2, -8
	s_ashr_i32 s15, s14, 8
	s_lshl_b32 s44, s16, 10
	s_sub_i32 s2, s0, s2
	s_cmp_lt_i32 s2, 0
	s_movk_i32 s5, 0xb1
	s_cselect_b32 s5, s5, 0xb0
	s_mul_i32 s2, s5, s2
	s_add_i32 s2, s2, s4
	s_mul_hi_i32 s4, s2, 0x2e8ba2e9
	s_lshr_b32 s5, s4, 31
	s_ashr_i32 s4, s4, 5
	s_add_i32 s4, s4, s5
	s_lshl_b32 s5, s4, 3
	s_mulk_i32 s4, 0xb0
	s_sub_i32 s4, s2, s4
	s_bfe_u32 s2, s4, 0x3001c
	s_add_i32 s12, s4, s2
	s_sext_i32_i16 s2, s12
	s_and_b32 s12, s12, 0xfff8
	v_lshrrev_b32_e32 v3, 2, v0
	v_lshlrev_b32_e32 v4, 1, v0
	s_sub_i32 s4, s4, s12
	v_and_b32_e32 v3, 4, v3
	v_and_b32_e32 v4, 24, v4
	s_sext_i32_i16 s4, s4
	v_or3_b32 v2, v2, v3, v4
	v_mul_i32_i24_e32 v4, 64, v12
	s_lshr_b32 s2, s2, 3
	s_add_i32 s26, s5, s4
	v_sub_u32_e32 v1, v1, v4
	s_ashr_i32 s27, s26, 31
	s_bfe_i64 s[4:5], s[2:3], 0x100000
	v_lshlrev_b32_e32 v3, 5, v13
	v_ashrrev_i16_sdwa v1, v237, sext(v1) dst_sel:DWORD dst_unused:UNUSED_PAD src0_sel:DWORD src1_sel:BYTE_0
	s_lshl_b64 s[12:13], s[26:27], 19
	s_lshl_b64 s[4:5], s[4:5], 19
	v_and_b32_e32 v3, 32, v3
	v_bfe_i32 v14, v1, 0, 16
	s_add_u32 s4, s6, s4
	v_add_lshl_u32 v1, v3, v14, 1
	s_addc_u32 s5, s7, s5
	s_add_i32 s27, s44, 0
	v_lshl_add_u32 v192, v2, 11, v1
	s_add_i32 m0, s27, 0x10000
	v_lshl_add_u32 v132, v0, 11, v1
	global_load_lds_dwordx4 v192, s[4:5]
	s_add_i32 m0, s27, 0x12000
	s_add_u32 s28, s4, 0x40000
	global_load_lds_dwordx4 v128, s[4:5]
	s_addc_u32 s29, s5, 0
	s_add_i32 m0, s27, 0x14000
	v_mov_b32_e32 v129, v193
	global_load_lds_dwordx4 v192, s[28:29]
	s_add_i32 m0, s27, 0x16000
	s_add_u32 s36, s1, s12
	s_addc_u32 s37, s42, s13
	s_add_i32 s45, s27, 0x2000
	global_load_lds_dwordx4 v128, s[28:29]
	s_mov_b32 m0, s27
	s_add_u32 s12, s36, 0x40000
	global_load_lds_dwordx4 v132, s[36:37]
	s_mov_b32 m0, s45
	s_addc_u32 s13, s37, 0
	s_add_i32 s46, s27, 0x4000
	global_load_lds_dwordx4 v130, s[36:37]
	s_mov_b32 m0, s46
	s_add_i32 s47, s27, 0x6000
	global_load_lds_dwordx4 v132, s[12:13]
	s_mov_b32 m0, s47
	v_mov_b32_e32 v133, v193
	global_load_lds_dwordx4 v130, s[12:13]
	s_load_dwordx2 s[12:13], s[10:11], 0x78
	v_mov_b32_e32 v131, v193
	s_cmp_eq_u32 s15, 1
	v_lshl_add_u64 v[6:7], s[4:5], 0, v[192:193]
	v_lshl_add_u64 v[4:5], s[4:5], 0, v[128:129]
	v_lshl_add_u64 v[0:1], s[36:37], 0, v[132:133]
	s_cselect_b64 s[10:11], -1, 0
	s_cmp_lg_u32 s15, 1
	v_lshl_add_u64 v[2:3], s[36:37], 0, v[130:131]
	s_cbranch_scc1 .LBB0_61
	s_barrier

.LBB0_66:
	s_ashr_i32 s29, s28, 31
	s_lshl_b64 s[30:31], s[28:29], 19
	s_add_u32 s30, s1, s30
	s_addc_u32 s31, s42, s31
	s_and_b64 s[34:35], s[38:39], exec
	s_cselect_b32 s29, s31, s37
	s_cselect_b32 s51, s30, s36
	s_ashr_i32 s17, s16, 31
	s_lshl_b64 s[34:35], s[16:17], 19
	s_add_u32 s34, s6, s34
	s_addc_u32 s35, s7, s35
	s_and_b64 s[40:41], s[38:39], exec
	s_cselect_b32 s17, s35, s5
	s_cselect_b32 s52, s34, s4
	s_add_u32 s36, s36, 0x40080
	s_addc_u32 s37, s37, 0
	s_add_u32 s53, s4, 0x100
	v_mov_b32_e32 v0, 0
	s_addc_u32 s54, s5, 0
	s_mov_b32 s55, -2
	v_mov_b32_e32 v1, v0
	v_mov_b32_e32 v2, v0
	v_mov_b32_e32 v3, v0
	v_mov_b32_e32 v4, v0
	v_mov_b32_e32 v5, v0
	v_mov_b32_e32 v6, v0
	v_mov_b32_e32 v7, v0
	v_mov_b32_e32 v16, v0
	v_mov_b32_e32 v17, v0
	v_mov_b32_e32 v18, v0
	v_mov_b32_e32 v19, v0
	v_mov_b32_e32 v20, v0
	v_mov_b32_e32 v21, v0
	v_mov_b32_e32 v22, v0
	v_mov_b32_e32 v23, v0
	v_mov_b32_e32 v32, v0
	v_mov_b32_e32 v33, v0
	v_mov_b32_e32 v34, v0
	v_mov_b32_e32 v35, v0
	v_mov_b32_e32 v36, v0
	v_mov_b32_e32 v37, v0
	v_mov_b32_e32 v38, v0
	v_mov_b32_e32 v39, v0
	v_mov_b32_e32 v48, v0
	v_mov_b32_e32 v49, v0
	v_mov_b32_e32 v50, v0
	v_mov_b32_e32 v51, v0
	v_mov_b32_e32 v52, v0
	v_mov_b32_e32 v53, v0
	v_mov_b32_e32 v54, v0
	v_mov_b32_e32 v55, v0
	v_mov_b32_e32 v8, v0
	v_mov_b32_e32 v9, v0
	v_mov_b32_e32 v10, v0
	v_mov_b32_e32 v11, v0
	v_mov_b32_e32 v12, v0
	v_mov_b32_e32 v13, v0
	v_mov_b32_e32 v14, v0
	v_mov_b32_e32 v15, v0
	v_mov_b32_e32 v24, v0
	v_mov_b32_e32 v25, v0
	v_mov_b32_e32 v26, v0
	v_mov_b32_e32 v27, v0
	v_mov_b32_e32 v28, v0
	v_mov_b32_e32 v29, v0
	v_mov_b32_e32 v30, v0
	v_mov_b32_e32 v31, v0
	v_mov_b32_e32 v40, v0
	v_mov_b32_e32 v41, v0
	v_mov_b32_e32 v42, v0
	v_mov_b32_e32 v43, v0
	v_mov_b32_e32 v44, v0
	v_mov_b32_e32 v45, v0
	v_mov_b32_e32 v46, v0
	v_mov_b32_e32 v47, v0
	v_mov_b32_e32 v56, v0
	v_mov_b32_e32 v57, v0
	v_mov_b32_e32 v58, v0
	v_mov_b32_e32 v59, v0
	v_mov_b32_e32 v60, v0
	v_mov_b32_e32 v61, v0
	v_mov_b32_e32 v62, v0
	v_mov_b32_e32 v63, v0
	v_mov_b32_e32 v64, v0
	v_mov_b32_e32 v65, v0
	v_mov_b32_e32 v66, v0
	v_mov_b32_e32 v67, v0
	v_mov_b32_e32 v68, v0
	v_mov_b32_e32 v69, v0
	v_mov_b32_e32 v70, v0
	v_mov_b32_e32 v71, v0
	v_mov_b32_e32 v80, v0
	v_mov_b32_e32 v81, v0
	v_mov_b32_e32 v82, v0
	v_mov_b32_e32 v83, v0
	v_mov_b32_e32 v84, v0
	v_mov_b32_e32 v85, v0
	v_mov_b32_e32 v86, v0
	v_mov_b32_e32 v87, v0
	v_mov_b32_e32 v96, v0
	v_mov_b32_e32 v97, v0
	v_mov_b32_e32 v98, v0
	v_mov_b32_e32 v99, v0
	v_mov_b32_e32 v100, v0
	v_mov_b32_e32 v101, v0
	v_mov_b32_e32 v102, v0
	v_mov_b32_e32 v103, v0
	v_mov_b32_e32 v112, v0
	v_mov_b32_e32 v113, v0
	v_mov_b32_e32 v114, v0
	v_mov_b32_e32 v115, v0
	v_mov_b32_e32 v116, v0
	v_mov_b32_e32 v117, v0
	v_mov_b32_e32 v118, v0
	v_mov_b32_e32 v119, v0
	v_mov_b32_e32 v72, v0
	v_mov_b32_e32 v73, v0
	v_mov_b32_e32 v74, v0
	v_mov_b32_e32 v75, v0
	v_mov_b32_e32 v76, v0
	v_mov_b32_e32 v77, v0
	v_mov_b32_e32 v78, v0
	v_mov_b32_e32 v79, v0
	v_mov_b32_e32 v88, v0
	v_mov_b32_e32 v89, v0
	v_mov_b32_e32 v90, v0
	v_mov_b32_e32 v91, v0
	v_mov_b32_e32 v92, v0
	v_mov_b32_e32 v93, v0
	v_mov_b32_e32 v94, v0
	v_mov_b32_e32 v95, v0
	v_mov_b32_e32 v104, v0
	v_mov_b32_e32 v105, v0
	v_mov_b32_e32 v106, v0
	v_mov_b32_e32 v107, v0
	v_mov_b32_e32 v108, v0
	v_mov_b32_e32 v109, v0
	v_mov_b32_e32 v110, v0
	v_mov_b32_e32 v111, v0
	v_mov_b32_e32 v120, v0
	v_mov_b32_e32 v121, v0
	v_mov_b32_e32 v122, v0
	v_mov_b32_e32 v123, v0
	v_mov_b32_e32 v124, v0
	v_mov_b32_e32 v125, v0
	v_mov_b32_e32 v126, v0
	v_mov_b32_e32 v127, v0
	s_cmp_eq_u32 s19, 1
	s_cbranch_scc0 .LBB0_67
	s_mov_b32 s19, 0
	s_add_u32 s4, s36, 0xfffc0080
	s_addc_u32 s5, s37, -1
	s_add_i32 s58, 0, 0x10000
	s_cmp_eq_u32 s55, 12
	s_cselect_b32 s41, s29, s5
	s_cselect_b32 s40, s51, s4
	v_add_u32_e32 v138, s58, v141
	s_cselect_b32 s5, s17, s54
	s_cselect_b32 s4, s52, s53
	s_add_i32 s60, 0, 0x14000
	ds_read_b128 v[144:147], v138
	ds_read_b128 v[148:151], v138 offset:1024
	ds_read_b128 v[152:155], v138 offset:2048
	ds_read_b128 v[156:159], v138 offset:3072
	v_add_u32_e32 v138, s60, v141
	ds_read_b128 v[160:163], v138
	ds_read_b128 v[164:167], v138 offset:1024
	ds_read_b128 v[168:171], v138 offset:2048
	ds_read_b128 v[172:175], v138 offset:3072
	v_lshl_add_u64 v[138:139], s[36:37], 0, v[134:135]
	s_add_i32 m0, s27, 0xc000
	ds_read_b128 v[176:179], v143
	ds_read_b128 v[180:183], v143 offset:1024
	ds_read_b128 v[184:187], v143 offset:2048
	ds_read_b128 v[188:191], v143 offset:3072
	ds_read_b128 v[208:211], v143 offset:4096
	ds_read_b128 v[212:215], v143 offset:5120
	ds_read_b128 v[216:219], v143 offset:6144
	ds_read_b128 v[220:223], v143 offset:7168
	global_load_lds_dwordx4 v[138:139], off
	v_lshl_add_u64 v[138:139], s[36:37], 0, v[136:137]
	s_add_i32 m0, s27, 0xe000
	s_nop 0
	global_load_lds_dwordx4 v[138:139], off
	s_waitcnt vmcnt(16)
	s_waitcnt lgkmcnt(0)
	s_barrier
	s_setprio 1
	s_waitcnt lgkmcnt(0)
	v_mfma_f32_16x16x32_bf16 v[124:127], v[144:147], v[176:179], v[124:127]
	v_mfma_f32_16x16x32_bf16 v[120:123], v[152:155], v[176:179], v[120:123]
	v_mfma_f32_16x16x32_bf16 v[108:111], v[144:147], v[184:187], v[108:111]
	v_mfma_f32_16x16x32_bf16 v[104:107], v[152:155], v[184:187], v[104:107]
	v_mfma_f32_16x16x32_bf16 v[92:95], v[144:147], v[208:211], v[92:95]
	v_mfma_f32_16x16x32_bf16 v[88:91], v[152:155], v[208:211], v[88:91]
	v_mfma_f32_16x16x32_bf16 v[76:79], v[144:147], v[216:219], v[76:79]
	v_mfma_f32_16x16x32_bf16 v[72:75], v[152:155], v[216:219], v[72:75]
	v_mfma_f32_16x16x32_bf16 v[124:127], v[148:151], v[180:183], v[124:127]
	v_mfma_f32_16x16x32_bf16 v[120:123], v[156:159], v[180:183], v[120:123]
	v_mfma_f32_16x16x32_bf16 v[108:111], v[148:151], v[188:191], v[108:111]
	v_mfma_f32_16x16x32_bf16 v[104:107], v[156:159], v[188:191], v[104:107]
	v_mfma_f32_16x16x32_bf16 v[92:95], v[148:151], v[212:215], v[92:95]
	v_mfma_f32_16x16x32_bf16 v[88:91], v[156:159], v[212:215], v[88:91]
	v_mfma_f32_16x16x32_bf16 v[76:79], v[148:151], v[220:223], v[76:79]
	v_mfma_f32_16x16x32_bf16 v[72:75], v[156:159], v[220:223], v[72:75]
	s_setprio 0
	s_setprio 1
	v_mfma_f32_16x16x32_bf16 v[116:119], v[160:163], v[176:179], v[116:119]
	v_mfma_f32_16x16x32_bf16 v[112:115], v[168:171], v[176:179], v[112:115]
	v_mfma_f32_16x16x32_bf16 v[100:103], v[160:163], v[184:187], v[100:103]
	v_mfma_f32_16x16x32_bf16 v[96:99], v[168:171], v[184:187], v[96:99]
	v_mfma_f32_16x16x32_bf16 v[84:87], v[160:163], v[208:211], v[84:87]
	v_mfma_f32_16x16x32_bf16 v[80:83], v[168:171], v[208:211], v[80:83]
	v_mfma_f32_16x16x32_bf16 v[68:71], v[160:163], v[216:219], v[68:71]
	v_mfma_f32_16x16x32_bf16 v[64:67], v[168:171], v[216:219], v[64:67]
	v_mfma_f32_16x16x32_bf16 v[116:119], v[164:167], v[180:183], v[116:119]
	v_mfma_f32_16x16x32_bf16 v[112:115], v[172:175], v[180:183], v[112:115]
	v_mfma_f32_16x16x32_bf16 v[100:103], v[164:167], v[188:191], v[100:103]
	v_mfma_f32_16x16x32_bf16 v[96:99], v[172:175], v[188:191], v[96:99]
	v_mfma_f32_16x16x32_bf16 v[84:87], v[164:167], v[212:215], v[84:87]
	v_mfma_f32_16x16x32_bf16 v[80:83], v[172:175], v[212:215], v[80:83]
	v_mfma_f32_16x16x32_bf16 v[68:71], v[164:167], v[220:223], v[68:71]
	v_mfma_f32_16x16x32_bf16 v[64:67], v[172:175], v[220:223], v[64:67]
	s_setprio 0
	s_barrier
	s_add_i32 s58, s58, s44
	v_lshl_add_u64 v[138:139], s[4:5], 0, v[192:193]
	s_mov_b32 m0, s58
	ds_read_b128 v[176:179], v143 offset:16384
	ds_read_b128 v[180:183], v143 offset:17408
	ds_read_b128 v[184:187], v143 offset:18432
	ds_read_b128 v[188:191], v143 offset:19456
	ds_read_b128 v[208:211], v143 offset:20480
	ds_read_b128 v[212:215], v143 offset:21504
	ds_read_b128 v[216:219], v143 offset:22528
	ds_read_b128 v[220:223], v143 offset:23552
	global_load_lds_dwordx4 v[138:139], off
	s_add_i32 m0, s58, 0x2000
	s_add_u32 s58, s4, 0x40000
	v_lshl_add_u64 v[224:225], s[4:5], 0, v[128:129]
	s_addc_u32 s59, s5, 0
	s_add_i32 s60, s60, s44
	global_load_lds_dwordx4 v[224:225], off
	v_lshl_add_u64 v[226:227], s[58:59], 0, v[192:193]
	s_mov_b32 m0, s60
	v_lshl_add_u64 v[228:229], s[40:41], 0, v[130:131]
	global_load_lds_dwordx4 v[226:227], off
	v_lshl_add_u64 v[226:227], s[58:59], 0, v[128:129]
	s_add_i32 m0, s60, 0x2000
	s_nop 0
	global_load_lds_dwordx4 v[226:227], off
	v_lshl_add_u64 v[226:227], s[40:41], 0, v[132:133]
	s_mov_b32 m0, s27
	s_nop 0
	global_load_lds_dwordx4 v[226:227], off
	s_mov_b32 m0, s45
	s_nop 0
	global_load_lds_dwordx4 v[228:229], off
	s_waitcnt vmcnt(16)
	s_branch .Lpeel_mid_up1

.Lpeel_mid_up1:
	s_waitcnt lgkmcnt(0)
	s_barrier
	s_setprio 1
	s_waitcnt lgkmcnt(0)
	v_mfma_f32_16x16x32_bf16 v[60:63], v[144:147], v[176:179], v[60:63]
	v_mfma_f32_16x16x32_bf16 v[56:59], v[152:155], v[176:179], v[56:59]
	v_mfma_f32_16x16x32_bf16 v[44:47], v[144:147], v[184:187], v[44:47]
	v_mfma_f32_16x16x32_bf16 v[40:43], v[152:155], v[184:187], v[40:43]
	v_mfma_f32_16x16x32_bf16 v[28:31], v[144:147], v[208:211], v[28:31]
	v_mfma_f32_16x16x32_bf16 v[24:27], v[152:155], v[208:211], v[24:27]
	v_mfma_f32_16x16x32_bf16 v[12:15], v[144:147], v[216:219], v[12:15]
	v_mfma_f32_16x16x32_bf16 v[8:11], v[152:155], v[216:219], v[8:11]
	v_mfma_f32_16x16x32_bf16 v[60:63], v[148:151], v[180:183], v[60:63]
	v_mfma_f32_16x16x32_bf16 v[56:59], v[156:159], v[180:183], v[56:59]
	v_mfma_f32_16x16x32_bf16 v[44:47], v[148:151], v[188:191], v[44:47]
	v_mfma_f32_16x16x32_bf16 v[40:43], v[156:159], v[188:191], v[40:43]
	v_mfma_f32_16x16x32_bf16 v[28:31], v[148:151], v[212:215], v[28:31]
	v_mfma_f32_16x16x32_bf16 v[24:27], v[156:159], v[212:215], v[24:27]
	v_mfma_f32_16x16x32_bf16 v[12:15], v[148:151], v[220:223], v[12:15]
	v_mfma_f32_16x16x32_bf16 v[8:11], v[156:159], v[220:223], v[8:11]
	s_setprio 0
	s_setprio 1
	v_mfma_f32_16x16x32_bf16 v[52:55], v[160:163], v[176:179], v[52:55]
	v_mfma_f32_16x16x32_bf16 v[48:51], v[168:171], v[176:179], v[48:51]
	v_mfma_f32_16x16x32_bf16 v[36:39], v[160:163], v[184:187], v[36:39]
	v_mfma_f32_16x16x32_bf16 v[32:35], v[168:171], v[184:187], v[32:35]
	v_mfma_f32_16x16x32_bf16 v[20:23], v[160:163], v[208:211], v[20:23]
	v_mfma_f32_16x16x32_bf16 v[16:19], v[168:171], v[208:211], v[16:19]
	v_mfma_f32_16x16x32_bf16 v[4:7], v[160:163], v[216:219], v[4:7]
	v_mfma_f32_16x16x32_bf16 v[0:3], v[168:171], v[216:219], v[0:3]
	v_mfma_f32_16x16x32_bf16 v[52:55], v[164:167], v[180:183], v[52:55]
	v_mfma_f32_16x16x32_bf16 v[48:51], v[172:175], v[180:183], v[48:51]
	v_mfma_f32_16x16x32_bf16 v[36:39], v[164:167], v[188:191], v[36:39]
	v_mfma_f32_16x16x32_bf16 v[32:35], v[172:175], v[188:191], v[32:35]
	v_mfma_f32_16x16x32_bf16 v[20:23], v[164:167], v[212:215], v[20:23]
	v_mfma_f32_16x16x32_bf16 v[16:19], v[172:175], v[212:215], v[16:19]
	v_mfma_f32_16x16x32_bf16 v[4:7], v[164:167], v[220:223], v[4:7]
	v_mfma_f32_16x16x32_bf16 v[0:3], v[172:175], v[220:223], v[0:3]
	s_setprio 0
	s_barrier
	s_add_i32 s58, 0, 0x18000
	s_add_i32 s59, 0, 0x1c000
	v_add_u32_e32 v156, s58, v141
	v_add_u32_e32 v172, s59, v141
	ds_read_b128 v[144:147], v156
	ds_read_b128 v[148:151], v156 offset:1024
	ds_read_b128 v[152:155], v156 offset:2048
	ds_read_b128 v[156:159], v156 offset:3072
	ds_read_b128 v[160:163], v172
	ds_read_b128 v[164:167], v172 offset:1024
	ds_read_b128 v[168:171], v172 offset:2048
	ds_read_b128 v[172:175], v172 offset:3072
	s_add_u32 s40, s40, 0x40000
	s_addc_u32 s41, s41, 0
	s_mov_b32 m0, s46
	v_lshl_add_u64 v[230:231], s[40:41], 0, v[132:133]
	ds_read_b128 v[176:179], v143 offset:32768
	ds_read_b128 v[180:183], v143 offset:33792
	ds_read_b128 v[184:187], v143 offset:34816
	ds_read_b128 v[188:191], v143 offset:35840
	ds_read_b128 v[208:211], v143 offset:36864
	ds_read_b128 v[212:215], v143 offset:37888
	ds_read_b128 v[216:219], v143 offset:38912
	ds_read_b128 v[220:223], v143 offset:39936
	global_load_lds_dwordx4 v[230:231], off
	v_lshl_add_u64 v[230:231], s[40:41], 0, v[130:131]
	s_mov_b32 m0, s47
	s_nop 0
	global_load_lds_dwordx4 v[230:231], off
	s_waitcnt vmcnt(8)
	s_waitcnt lgkmcnt(0)
	s_barrier
	s_setprio 1
	s_waitcnt lgkmcnt(0)
	v_mfma_f32_16x16x32_bf16 v[124:127], v[144:147], v[176:179], v[124:127]
	v_mfma_f32_16x16x32_bf16 v[120:123], v[152:155], v[176:179], v[120:123]
	v_mfma_f32_16x16x32_bf16 v[108:111], v[144:147], v[184:187], v[108:111]
	v_mfma_f32_16x16x32_bf16 v[104:107], v[152:155], v[184:187], v[104:107]
	v_mfma_f32_16x16x32_bf16 v[92:95], v[144:147], v[208:211], v[92:95]
	v_mfma_f32_16x16x32_bf16 v[88:91], v[152:155], v[208:211], v[88:91]
	v_mfma_f32_16x16x32_bf16 v[76:79], v[144:147], v[216:219], v[76:79]
	v_mfma_f32_16x16x32_bf16 v[72:75], v[152:155], v[216:219], v[72:75]
	v_mfma_f32_16x16x32_bf16 v[124:127], v[148:151], v[180:183], v[124:127]
	v_mfma_f32_16x16x32_bf16 v[120:123], v[156:159], v[180:183], v[120:123]
	v_mfma_f32_16x16x32_bf16 v[108:111], v[148:151], v[188:191], v[108:111]
	v_mfma_f32_16x16x32_bf16 v[104:107], v[156:159], v[188:191], v[104:107]
	v_mfma_f32_16x16x32_bf16 v[92:95], v[148:151], v[212:215], v[92:95]
	v_mfma_f32_16x16x32_bf16 v[88:91], v[156:159], v[212:215], v[88:91]
	v_mfma_f32_16x16x32_bf16 v[76:79], v[148:151], v[220:223], v[76:79]
	v_mfma_f32_16x16x32_bf16 v[72:75], v[156:159], v[220:223], v[72:75]
	s_setprio 0
	s_setprio 1
	v_mfma_f32_16x16x32_bf16 v[116:119], v[160:163], v[176:179], v[116:119]
	v_mfma_f32_16x16x32_bf16 v[112:115], v[168:171], v[176:179], v[112:115]
	v_mfma_f32_16x16x32_bf16 v[100:103], v[160:163], v[184:187], v[100:103]
	v_mfma_f32_16x16x32_bf16 v[96:99], v[168:171], v[184:187], v[96:99]
	v_mfma_f32_16x16x32_bf16 v[84:87], v[160:163], v[208:211], v[84:87]
	v_mfma_f32_16x16x32_bf16 v[80:83], v[168:171], v[208:211], v[80:83]
	v_mfma_f32_16x16x32_bf16 v[68:71], v[160:163], v[216:219], v[68:71]
	v_mfma_f32_16x16x32_bf16 v[64:67], v[168:171], v[216:219], v[64:67]
	v_mfma_f32_16x16x32_bf16 v[116:119], v[164:167], v[180:183], v[116:119]
	v_mfma_f32_16x16x32_bf16 v[112:115], v[172:175], v[180:183], v[112:115]
	v_mfma_f32_16x16x32_bf16 v[100:103], v[164:167], v[188:191], v[100:103]
	v_mfma_f32_16x16x32_bf16 v[96:99], v[172:175], v[188:191], v[96:99]
	v_mfma_f32_16x16x32_bf16 v[84:87], v[164:167], v[212:215], v[84:87]
	v_mfma_f32_16x16x32_bf16 v[80:83], v[172:175], v[212:215], v[80:83]
	v_mfma_f32_16x16x32_bf16 v[68:71], v[164:167], v[220:223], v[68:71]
	v_mfma_f32_16x16x32_bf16 v[64:67], v[172:175], v[220:223], v[64:67]
	s_setprio 0
	s_barrier
	s_add_i32 s40, s58, s44
	v_lshl_add_u64 v[138:139], v[138:139], 0, s[8:9]
	s_mov_b32 m0, s40
	ds_read_b128 v[176:179], v143 offset:49152
	ds_read_b128 v[180:183], v143 offset:50176
	ds_read_b128 v[184:187], v143 offset:51200
	ds_read_b128 v[188:191], v143 offset:52224
	ds_read_b128 v[208:211], v143 offset:53248
	ds_read_b128 v[212:215], v143 offset:54272
	ds_read_b128 v[216:219], v143 offset:55296
	ds_read_b128 v[220:223], v143 offset:56320
	global_load_lds_dwordx4 v[138:139], off
	s_add_i32 m0, s40, 0x2000
	s_add_u32 s4, s4, 0x40080
	v_lshl_add_u64 v[138:139], v[224:225], 0, s[8:9]
	s_addc_u32 s5, s5, 0
	s_add_i32 s40, s59, s44
	global_load_lds_dwordx4 v[138:139], off
	v_lshl_add_u64 v[138:139], s[4:5], 0, v[192:193]
	s_mov_b32 m0, s40
	s_nop 0
	global_load_lds_dwordx4 v[138:139], off
	v_lshl_add_u64 v[138:139], s[4:5], 0, v[128:129]
	s_add_i32 m0, s40, 0x2000
	s_nop 0
	global_load_lds_dwordx4 v[138:139], off
	v_lshl_add_u64 v[138:139], v[226:227], 0, s[8:9]
	s_mov_b32 m0, s48
	s_nop 0
	global_load_lds_dwordx4 v[138:139], off
	v_lshl_add_u64 v[138:139], v[228:229], 0, s[8:9]
	s_mov_b32 m0, s49
	s_nop 0
	global_load_lds_dwordx4 v[138:139], off
	s_waitcnt vmcnt(8)
	s_waitcnt lgkmcnt(0)
	s_barrier
	s_setprio 1
	s_waitcnt lgkmcnt(0)
	v_mfma_f32_16x16x32_bf16 v[60:63], v[144:147], v[176:179], v[60:63]
	v_mfma_f32_16x16x32_bf16 v[56:59], v[152:155], v[176:179], v[56:59]
	v_mfma_f32_16x16x32_bf16 v[44:47], v[144:147], v[184:187], v[44:47]
	v_mfma_f32_16x16x32_bf16 v[40:43], v[152:155], v[184:187], v[40:43]
	v_mfma_f32_16x16x32_bf16 v[28:31], v[144:147], v[208:211], v[28:31]
	v_mfma_f32_16x16x32_bf16 v[24:27], v[152:155], v[208:211], v[24:27]
	v_mfma_f32_16x16x32_bf16 v[12:15], v[144:147], v[216:219], v[12:15]
	v_mfma_f32_16x16x32_bf16 v[8:11], v[152:155], v[216:219], v[8:11]
	v_mfma_f32_16x16x32_bf16 v[60:63], v[148:151], v[180:183], v[60:63]
	v_mfma_f32_16x16x32_bf16 v[56:59], v[156:159], v[180:183], v[56:59]
	v_mfma_f32_16x16x32_bf16 v[44:47], v[148:151], v[188:191], v[44:47]
	v_mfma_f32_16x16x32_bf16 v[40:43], v[156:159], v[188:191], v[40:43]
	v_mfma_f32_16x16x32_bf16 v[28:31], v[148:151], v[212:215], v[28:31]
	v_mfma_f32_16x16x32_bf16 v[24:27], v[156:159], v[212:215], v[24:27]
	v_mfma_f32_16x16x32_bf16 v[12:15], v[148:151], v[220:223], v[12:15]
	v_mfma_f32_16x16x32_bf16 v[8:11], v[156:159], v[220:223], v[8:11]
	s_setprio 0
	s_setprio 1
	v_mfma_f32_16x16x32_bf16 v[52:55], v[160:163], v[176:179], v[52:55]
	v_mfma_f32_16x16x32_bf16 v[48:51], v[168:171], v[176:179], v[48:51]
	v_mfma_f32_16x16x32_bf16 v[36:39], v[160:163], v[184:187], v[36:39]
	v_mfma_f32_16x16x32_bf16 v[32:35], v[168:171], v[184:187], v[32:35]
	v_mfma_f32_16x16x32_bf16 v[20:23], v[160:163], v[208:211], v[20:23]
	v_mfma_f32_16x16x32_bf16 v[16:19], v[168:171], v[208:211], v[16:19]
	v_mfma_f32_16x16x32_bf16 v[4:7], v[160:163], v[216:219], v[4:7]
	v_mfma_f32_16x16x32_bf16 v[0:3], v[168:171], v[216:219], v[0:3]
	v_mfma_f32_16x16x32_bf16 v[52:55], v[164:167], v[180:183], v[52:55]
	v_mfma_f32_16x16x32_bf16 v[48:51], v[172:175], v[180:183], v[48:51]
	v_mfma_f32_16x16x32_bf16 v[36:39], v[164:167], v[188:191], v[36:39]
	v_mfma_f32_16x16x32_bf16 v[32:35], v[172:175], v[188:191], v[32:35]
	v_mfma_f32_16x16x32_bf16 v[20:23], v[164:167], v[212:215], v[20:23]
	v_mfma_f32_16x16x32_bf16 v[16:19], v[172:175], v[212:215], v[16:19]
	v_mfma_f32_16x16x32_bf16 v[4:7], v[164:167], v[220:223], v[4:7]
	v_mfma_f32_16x16x32_bf16 v[0:3], v[172:175], v[220:223], v[0:3]
	s_setprio 0
	s_barrier
	s_add_i32 s55, s55, 2
	s_add_u32 s36, s36, 0x100
	s_addc_u32 s37, s37, 0
	s_add_u32 s53, s53, 0x100
	s_addc_u32 s54, s54, 0
	s_cmp_gt_u32 s55, 13
	s_cbranch_scc0 .LBB0_67
	s_and_b64 vcc, exec, s[14:15]
	s_cbranch_vccz .LBB0_70
	s_barrier
.LBB0_70:
	v_mul_f32_e32 v138, 0xbfb8aa3b, v124
	v_exp_f32_e32 v138, v138
	v_mul_f32_e32 v139, 0xbfb8aa3b, v125
	v_exp_f32_e32 v139, v139
	v_mul_f32_e32 v145, 0xbfb8aa3b, v126
	v_add_f32_e32 v138, 1.0, v138
	v_rcp_f32_e32 v148, v138
	v_add_f32_e32 v138, 1.0, v139
	v_rcp_f32_e32 v149, v138
	v_exp_f32_e32 v145, v145
	v_lshl_or_b32 v146, s50, 7, v142
	v_lshl_add_u32 v144, s26, 8, v140
	v_pk_mul_f32 v[124:125], v[124:125], v[148:149]
	v_mul_f32_e32 v148, 0xbfb8aa3b, v127
	v_exp_f32_e32 v148, v148
	v_pk_mul_f32 v[116:117], v[124:125], v[116:117]
	v_add_f32_e32 v124, 1.0, v145
	v_mul_f32_e32 v145, 0xbfb8aa3b, v120
	v_add_f32_e32 v125, 1.0, v148
	v_rcp_f32_e32 v124, v124
	v_rcp_f32_e32 v125, v125
	v_exp_f32_e32 v145, v145
	v_mul_f32_e32 v148, 0xbfb8aa3b, v121
	v_exp_f32_e32 v148, v148
	v_pk_mul_f32 v[124:125], v[126:127], v[124:125]
	v_add_f32_e32 v126, 1.0, v145
	v_mul_f32_e32 v145, 0xbfb8aa3b, v122
	v_add_f32_e32 v127, 1.0, v148
	v_exp_f32_e32 v145, v145
	v_mul_f32_e32 v148, 0xbfb8aa3b, v123
	v_exp_f32_e32 v149, v148
	v_rcp_f32_e32 v126, v126
	v_add_f32_e32 v145, 1.0, v145
	v_rcp_f32_e32 v127, v127
	v_rcp_f32_e32 v148, v145
	v_add_f32_e32 v145, 1.0, v149
	v_rcp_f32_e32 v149, v145
	v_pk_mul_f32 v[120:121], v[120:121], v[126:127]
	v_pk_mul_f32 v[118:119], v[124:125], v[118:119]
	v_pk_mul_f32 v[120:121], v[120:121], v[112:113]
	v_pk_mul_f32 v[112:113], v[122:123], v[148:149]
	v_ashrrev_i32_e32 v147, 31, v146
	v_pk_mul_f32 v[122:123], v[112:113], v[114:115]
	v_cvt_pk_bf16_f32 v115, v118, v119
	v_mul_f32_e32 v118, 0xbfb8aa3b, v108
	v_mul_f32_e32 v119, 0xbfb8aa3b, v109
	v_exp_f32_e32 v118, v118
	v_exp_f32_e32 v119, v119
	v_mov_b64_e32 v[138:139], s[12:13]
	v_mad_i64_i32 v[150:151], s[4:5], v144, s33, v[138:139]
	v_lshlrev_b64 v[112:113], 1, v[146:147]
	v_lshl_add_u64 v[124:125], v[150:151], 0, v[112:113]
	v_cvt_pk_bf16_f32 v114, v116, v117
	v_cvt_pk_bf16_f32 v116, v120, v121
	v_cvt_pk_bf16_f32 v117, v122, v123
	global_store_dwordx4 v[124:125], v[114:117], off
	s_andn2_b64 vcc, exec, s[38:39]
	s_nop 0
	v_add_f32_e32 v114, 1.0, v118
	v_add_f32_e32 v115, 1.0, v119
	v_rcp_f32_e32 v114, v114
	v_rcp_f32_e32 v115, v115
	v_or_b32_e32 v116, 16, v144
	v_mad_i64_i32 v[116:117], s[4:5], v116, s33, v[138:139]
	v_pk_mul_f32 v[108:109], v[108:109], v[114:115]
	v_mul_f32_e32 v114, 0xbfb8aa3b, v110
	v_mul_f32_e32 v115, 0xbfb8aa3b, v111
	v_exp_f32_e32 v114, v114
	v_exp_f32_e32 v115, v115
	v_pk_mul_f32 v[100:101], v[108:109], v[100:101]
	v_add_f32_e32 v108, 1.0, v114
	v_add_f32_e32 v109, 1.0, v115
	v_mul_f32_e32 v114, 0xbfb8aa3b, v104
	v_mul_f32_e32 v115, 0xbfb8aa3b, v105
	v_rcp_f32_e32 v108, v108
	v_rcp_f32_e32 v109, v109
	v_exp_f32_e32 v114, v114
	v_exp_f32_e32 v115, v115
	v_pk_mul_f32 v[108:109], v[110:111], v[108:109]
	v_add_f32_e32 v110, 1.0, v114
	v_add_f32_e32 v111, 1.0, v115
	v_mul_f32_e32 v114, 0xbfb8aa3b, v106
	v_mul_f32_e32 v115, 0xbfb8aa3b, v107
	v_exp_f32_e32 v114, v114
	v_exp_f32_e32 v115, v115
	v_rcp_f32_e32 v110, v110
	v_rcp_f32_e32 v111, v111
	v_add_f32_e32 v114, 1.0, v114
	v_add_f32_e32 v115, 1.0, v115
	v_rcp_f32_e32 v114, v114
	v_rcp_f32_e32 v115, v115
	v_pk_mul_f32 v[104:105], v[104:105], v[110:111]
	v_pk_mul_f32 v[102:103], v[108:109], v[102:103]
	v_pk_mul_f32 v[104:105], v[104:105], v[96:97]
	v_pk_mul_f32 v[96:97], v[106:107], v[114:115]
	v_lshl_add_u64 v[108:109], v[116:117], 0, v[112:113]
	v_pk_mul_f32 v[106:107], v[96:97], v[98:99]
	v_cvt_pk_bf16_f32 v96, v100, v101
	v_mul_f32_e32 v100, 0xbfb8aa3b, v92
	v_mul_f32_e32 v101, 0xbfb8aa3b, v93
	v_exp_f32_e32 v100, v100
	v_exp_f32_e32 v101, v101
	v_cvt_pk_bf16_f32 v97, v102, v103
	v_cvt_pk_bf16_f32 v98, v104, v105
	v_cvt_pk_bf16_f32 v99, v106, v107
	global_store_dwordx4 v[108:109], v[96:99], off
	s_nop 1
	v_add_f32_e32 v96, 1.0, v100
	v_add_f32_e32 v97, 1.0, v101
	v_rcp_f32_e32 v96, v96
	v_rcp_f32_e32 v97, v97
	v_or_b32_e32 v98, 32, v144
	v_mad_i64_i32 v[98:99], s[4:5], v98, s33, v[138:139]
	v_pk_mul_f32 v[92:93], v[92:93], v[96:97]
	v_mul_f32_e32 v96, 0xbfb8aa3b, v94
	v_mul_f32_e32 v97, 0xbfb8aa3b, v95
	v_exp_f32_e32 v96, v96
	v_exp_f32_e32 v97, v97
	v_pk_mul_f32 v[84:85], v[92:93], v[84:85]
	v_add_f32_e32 v92, 1.0, v96
	v_add_f32_e32 v93, 1.0, v97
	v_mul_f32_e32 v96, 0xbfb8aa3b, v88
	v_mul_f32_e32 v97, 0xbfb8aa3b, v89
	v_rcp_f32_e32 v92, v92
	v_rcp_f32_e32 v93, v93
	v_exp_f32_e32 v96, v96
	v_exp_f32_e32 v97, v97
	v_pk_mul_f32 v[92:93], v[94:95], v[92:93]
	v_add_f32_e32 v94, 1.0, v96
	v_add_f32_e32 v95, 1.0, v97
	v_mul_f32_e32 v96, 0xbfb8aa3b, v90
	v_mul_f32_e32 v97, 0xbfb8aa3b, v91
	v_exp_f32_e32 v96, v96
	v_exp_f32_e32 v97, v97
	v_rcp_f32_e32 v94, v94
	v_rcp_f32_e32 v95, v95
	v_add_f32_e32 v96, 1.0, v96
	v_add_f32_e32 v97, 1.0, v97
	v_rcp_f32_e32 v96, v96
	v_rcp_f32_e32 v97, v97
	v_pk_mul_f32 v[88:89], v[88:89], v[94:95]
	v_pk_mul_f32 v[86:87], v[92:93], v[86:87]
	v_pk_mul_f32 v[88:89], v[88:89], v[80:81]
	v_pk_mul_f32 v[80:81], v[90:91], v[96:97]
	v_lshl_add_u64 v[92:93], v[98:99], 0, v[112:113]
	v_pk_mul_f32 v[90:91], v[80:81], v[82:83]
	v_cvt_pk_bf16_f32 v80, v84, v85
	v_mul_f32_e32 v84, 0xbfb8aa3b, v76
	v_mul_f32_e32 v85, 0xbfb8aa3b, v77
	v_exp_f32_e32 v84, v84
	v_exp_f32_e32 v85, v85
	v_cvt_pk_bf16_f32 v81, v86, v87
	v_cvt_pk_bf16_f32 v82, v88, v89
	v_cvt_pk_bf16_f32 v83, v90, v91
	global_store_dwordx4 v[92:93], v[80:83], off
	s_nop 1
	v_add_f32_e32 v80, 1.0, v84
	v_add_f32_e32 v81, 1.0, v85
	v_rcp_f32_e32 v80, v80
	v_rcp_f32_e32 v81, v81
	v_or_b32_e32 v82, 48, v144
	v_mad_i64_i32 v[82:83], s[4:5], v82, s33, v[138:139]
	v_pk_mul_f32 v[76:77], v[76:77], v[80:81]
	v_mul_f32_e32 v80, 0xbfb8aa3b, v78
	v_mul_f32_e32 v81, 0xbfb8aa3b, v79
	v_exp_f32_e32 v80, v80
	v_exp_f32_e32 v81, v81
	v_pk_mul_f32 v[68:69], v[76:77], v[68:69]
	v_add_f32_e32 v76, 1.0, v80
	v_add_f32_e32 v77, 1.0, v81
	v_mul_f32_e32 v80, 0xbfb8aa3b, v72
	v_mul_f32_e32 v81, 0xbfb8aa3b, v73
	v_rcp_f32_e32 v76, v76
	v_rcp_f32_e32 v77, v77
	v_exp_f32_e32 v80, v80
	v_exp_f32_e32 v81, v81
	v_pk_mul_f32 v[76:77], v[78:79], v[76:77]
	v_add_f32_e32 v78, 1.0, v80
	v_add_f32_e32 v79, 1.0, v81
	v_mul_f32_e32 v80, 0xbfb8aa3b, v74
	v_mul_f32_e32 v81, 0xbfb8aa3b, v75
	v_exp_f32_e32 v80, v80
	v_exp_f32_e32 v81, v81
	v_rcp_f32_e32 v78, v78
	v_rcp_f32_e32 v79, v79
	v_add_f32_e32 v80, 1.0, v80
	v_add_f32_e32 v81, 1.0, v81
	v_rcp_f32_e32 v80, v80
	v_rcp_f32_e32 v81, v81
	v_pk_mul_f32 v[72:73], v[72:73], v[78:79]
	v_pk_mul_f32 v[70:71], v[76:77], v[70:71]
	v_pk_mul_f32 v[72:73], v[72:73], v[64:65]
	v_pk_mul_f32 v[64:65], v[74:75], v[80:81]
	v_lshl_add_u64 v[76:77], v[82:83], 0, v[112:113]
	v_pk_mul_f32 v[74:75], v[64:65], v[66:67]
	v_cvt_pk_bf16_f32 v64, v68, v69
	v_mul_f32_e32 v68, 0xbfb8aa3b, v60
	v_mul_f32_e32 v69, 0xbfb8aa3b, v61
	v_exp_f32_e32 v68, v68
	v_exp_f32_e32 v69, v69
	v_cvt_pk_bf16_f32 v65, v70, v71
	v_cvt_pk_bf16_f32 v66, v72, v73
	v_cvt_pk_bf16_f32 v67, v74, v75
	global_store_dwordx4 v[76:77], v[64:67], off
	s_nop 1
	v_add_f32_e32 v64, 1.0, v68
	v_add_f32_e32 v65, 1.0, v69
	v_rcp_f32_e32 v64, v64
	v_rcp_f32_e32 v65, v65
	v_add_u32_e32 v66, 0x80, v144
	v_mad_i64_i32 v[66:67], s[4:5], v66, s33, v[138:139]
	v_pk_mul_f32 v[60:61], v[60:61], v[64:65]
	v_mul_f32_e32 v64, 0xbfb8aa3b, v62
	v_mul_f32_e32 v65, 0xbfb8aa3b, v63
	v_exp_f32_e32 v64, v64
	v_exp_f32_e32 v65, v65
	v_pk_mul_f32 v[52:53], v[60:61], v[52:53]
	v_add_f32_e32 v60, 1.0, v64
	v_add_f32_e32 v61, 1.0, v65
	v_mul_f32_e32 v64, 0xbfb8aa3b, v56
	v_mul_f32_e32 v65, 0xbfb8aa3b, v57
	v_rcp_f32_e32 v60, v60
	v_rcp_f32_e32 v61, v61
	v_exp_f32_e32 v64, v64
	v_exp_f32_e32 v65, v65
	v_pk_mul_f32 v[60:61], v[62:63], v[60:61]
	v_add_f32_e32 v62, 1.0, v64
	v_add_f32_e32 v63, 1.0, v65
	v_mul_f32_e32 v64, 0xbfb8aa3b, v58
	v_mul_f32_e32 v65, 0xbfb8aa3b, v59
	v_exp_f32_e32 v64, v64
	v_exp_f32_e32 v65, v65
	v_rcp_f32_e32 v62, v62
	v_rcp_f32_e32 v63, v63
	v_add_f32_e32 v64, 1.0, v64
	v_add_f32_e32 v65, 1.0, v65
	v_rcp_f32_e32 v64, v64
	v_rcp_f32_e32 v65, v65
	v_pk_mul_f32 v[56:57], v[56:57], v[62:63]
	v_pk_mul_f32 v[54:55], v[60:61], v[54:55]
	v_pk_mul_f32 v[56:57], v[56:57], v[48:49]
	v_pk_mul_f32 v[48:49], v[58:59], v[64:65]
	v_lshl_add_u64 v[60:61], v[66:67], 0, v[112:113]
	v_pk_mul_f32 v[58:59], v[48:49], v[50:51]
	v_cvt_pk_bf16_f32 v48, v52, v53
	v_mul_f32_e32 v52, 0xbfb8aa3b, v44
	v_mul_f32_e32 v53, 0xbfb8aa3b, v45
	v_exp_f32_e32 v52, v52
	v_exp_f32_e32 v53, v53
	v_cvt_pk_bf16_f32 v49, v54, v55
	v_cvt_pk_bf16_f32 v50, v56, v57
	v_cvt_pk_bf16_f32 v51, v58, v59
	global_store_dwordx4 v[60:61], v[48:51], off
	s_nop 1
	v_add_f32_e32 v48, 1.0, v52
	v_add_f32_e32 v49, 1.0, v53
	v_rcp_f32_e32 v48, v48
	v_rcp_f32_e32 v49, v49
	v_add_u32_e32 v50, 0x90, v144
	v_mad_i64_i32 v[50:51], s[4:5], v50, s33, v[138:139]
	v_pk_mul_f32 v[44:45], v[44:45], v[48:49]
	v_mul_f32_e32 v48, 0xbfb8aa3b, v46
	v_mul_f32_e32 v49, 0xbfb8aa3b, v47
	v_exp_f32_e32 v48, v48
	v_exp_f32_e32 v49, v49
	v_pk_mul_f32 v[36:37], v[44:45], v[36:37]
	v_add_f32_e32 v44, 1.0, v48
	v_add_f32_e32 v45, 1.0, v49
	v_mul_f32_e32 v48, 0xbfb8aa3b, v40
	v_mul_f32_e32 v49, 0xbfb8aa3b, v41
	v_rcp_f32_e32 v44, v44
	v_rcp_f32_e32 v45, v45
	v_exp_f32_e32 v48, v48
	v_exp_f32_e32 v49, v49
	v_pk_mul_f32 v[44:45], v[46:47], v[44:45]
	v_add_f32_e32 v46, 1.0, v48
	v_add_f32_e32 v47, 1.0, v49
	v_mul_f32_e32 v48, 0xbfb8aa3b, v42
	v_mul_f32_e32 v49, 0xbfb8aa3b, v43
	v_exp_f32_e32 v48, v48
	v_exp_f32_e32 v49, v49
	v_rcp_f32_e32 v46, v46
	v_rcp_f32_e32 v47, v47
	v_add_f32_e32 v48, 1.0, v48
	v_add_f32_e32 v49, 1.0, v49
	v_rcp_f32_e32 v48, v48
	v_rcp_f32_e32 v49, v49
	v_pk_mul_f32 v[40:41], v[40:41], v[46:47]
	v_pk_mul_f32 v[38:39], v[44:45], v[38:39]
	v_pk_mul_f32 v[40:41], v[40:41], v[32:33]
	v_pk_mul_f32 v[32:33], v[42:43], v[48:49]
	v_lshl_add_u64 v[44:45], v[50:51], 0, v[112:113]
	v_pk_mul_f32 v[42:43], v[32:33], v[34:35]
	v_cvt_pk_bf16_f32 v32, v36, v37
	v_mul_f32_e32 v36, 0xbfb8aa3b, v28
	v_mul_f32_e32 v37, 0xbfb8aa3b, v29
	v_exp_f32_e32 v36, v36
	v_exp_f32_e32 v37, v37
	v_cvt_pk_bf16_f32 v33, v38, v39
	v_cvt_pk_bf16_f32 v34, v40, v41
	v_cvt_pk_bf16_f32 v35, v42, v43
	global_store_dwordx4 v[44:45], v[32:35], off
	s_nop 1
	v_add_f32_e32 v32, 1.0, v36
	v_add_f32_e32 v33, 1.0, v37
	v_rcp_f32_e32 v32, v32
	v_rcp_f32_e32 v33, v33
	v_add_u32_e32 v34, 0xa0, v144
	v_mad_i64_i32 v[34:35], s[4:5], v34, s33, v[138:139]
	v_pk_mul_f32 v[28:29], v[28:29], v[32:33]
	v_mul_f32_e32 v32, 0xbfb8aa3b, v30
	v_mul_f32_e32 v33, 0xbfb8aa3b, v31
	v_exp_f32_e32 v32, v32
	v_exp_f32_e32 v33, v33
	v_pk_mul_f32 v[20:21], v[28:29], v[20:21]
	v_add_f32_e32 v28, 1.0, v32
	v_add_f32_e32 v29, 1.0, v33
	v_mul_f32_e32 v32, 0xbfb8aa3b, v24
	v_mul_f32_e32 v33, 0xbfb8aa3b, v25
	v_rcp_f32_e32 v28, v28
	v_rcp_f32_e32 v29, v29
	v_exp_f32_e32 v32, v32
	v_exp_f32_e32 v33, v33
	v_pk_mul_f32 v[28:29], v[30:31], v[28:29]
	v_add_f32_e32 v30, 1.0, v32
	v_add_f32_e32 v31, 1.0, v33
	v_mul_f32_e32 v32, 0xbfb8aa3b, v26
	v_mul_f32_e32 v33, 0xbfb8aa3b, v27
	v_exp_f32_e32 v32, v32
	v_exp_f32_e32 v33, v33
	v_rcp_f32_e32 v30, v30
	v_rcp_f32_e32 v31, v31
	v_add_f32_e32 v32, 1.0, v32
	v_add_f32_e32 v33, 1.0, v33
	v_rcp_f32_e32 v32, v32
	v_rcp_f32_e32 v33, v33
	v_pk_mul_f32 v[24:25], v[24:25], v[30:31]
	v_pk_mul_f32 v[22:23], v[28:29], v[22:23]
	v_pk_mul_f32 v[24:25], v[24:25], v[16:17]
	v_pk_mul_f32 v[16:17], v[26:27], v[32:33]
	v_lshl_add_u64 v[28:29], v[34:35], 0, v[112:113]
	v_pk_mul_f32 v[26:27], v[16:17], v[18:19]
	v_cvt_pk_bf16_f32 v16, v20, v21
	v_mul_f32_e32 v20, 0xbfb8aa3b, v12
	v_mul_f32_e32 v21, 0xbfb8aa3b, v13
	v_exp_f32_e32 v20, v20
	v_exp_f32_e32 v21, v21
	v_cvt_pk_bf16_f32 v17, v22, v23
	v_cvt_pk_bf16_f32 v18, v24, v25
	v_cvt_pk_bf16_f32 v19, v26, v27
	global_store_dwordx4 v[28:29], v[16:19], off
	s_nop 1
	v_add_f32_e32 v16, 1.0, v20
	v_add_f32_e32 v17, 1.0, v21
	v_rcp_f32_e32 v16, v16
	v_rcp_f32_e32 v17, v17
	v_add_u32_e32 v18, 0xb0, v144
	v_mad_i64_i32 v[18:19], s[4:5], v18, s33, v[138:139]
	v_pk_mul_f32 v[12:13], v[12:13], v[16:17]
	v_mul_f32_e32 v16, 0xbfb8aa3b, v14
	v_mul_f32_e32 v17, 0xbfb8aa3b, v15
	v_exp_f32_e32 v16, v16
	v_exp_f32_e32 v17, v17
	v_pk_mul_f32 v[4:5], v[12:13], v[4:5]
	s_mov_b64 s[4:5], -1
	v_add_f32_e32 v12, 1.0, v16
	v_add_f32_e32 v13, 1.0, v17
	v_mul_f32_e32 v16, 0xbfb8aa3b, v8
	v_mul_f32_e32 v17, 0xbfb8aa3b, v9
	v_rcp_f32_e32 v12, v12
	v_rcp_f32_e32 v13, v13
	v_exp_f32_e32 v16, v16
	v_exp_f32_e32 v17, v17
	v_pk_mul_f32 v[12:13], v[14:15], v[12:13]
	v_add_f32_e32 v14, 1.0, v16
	v_add_f32_e32 v15, 1.0, v17
	v_mul_f32_e32 v16, 0xbfb8aa3b, v10
	v_mul_f32_e32 v17, 0xbfb8aa3b, v11
	v_exp_f32_e32 v16, v16
	v_exp_f32_e32 v17, v17
	v_rcp_f32_e32 v14, v14
	v_rcp_f32_e32 v15, v15
	v_add_f32_e32 v16, 1.0, v16
	v_add_f32_e32 v17, 1.0, v17
	v_rcp_f32_e32 v16, v16
	v_rcp_f32_e32 v17, v17
	v_pk_mul_f32 v[8:9], v[8:9], v[14:15]
	v_pk_mul_f32 v[6:7], v[12:13], v[6:7]
	v_pk_mul_f32 v[8:9], v[8:9], v[0:1]
	v_pk_mul_f32 v[0:1], v[10:11], v[16:17]
	v_lshl_add_u64 v[12:13], v[18:19], 0, v[112:113]
	v_pk_mul_f32 v[10:11], v[0:1], v[2:3]
	v_cvt_pk_bf16_f32 v0, v4, v5
	v_cvt_pk_bf16_f32 v1, v6, v7
	v_cvt_pk_bf16_f32 v2, v8, v9
	v_cvt_pk_bf16_f32 v3, v10, v11
	global_store_dwordx4 v[12:13], v[0:3], off
	s_mov_b32 s19, 1
	s_cbranch_vccnz .LBB0_63
	s_andn2_b64 vcc, exec, s[10:11]
	s_cbranch_vccnz .LBB0_62
	s_barrier
	s_branch .LBB0_62
.LBB0_73:
	s_mov_b32 s19, 0
	s_waitcnt vmcnt(0)
	v_readlane_b32 s28, v252, 11
	v_readlane_b32 s29, v252, 12
	s_barrier

.LBB0_936:
	s_ashr_i32 s17, s16, 31
	s_lshl_b64 s[28:29], s[16:17], 19
	s_add_u32 s28, s1, s28
	s_addc_u32 s29, s40, s29
	s_and_b64 s[30:31], s[38:39], exec
	s_cselect_b32 s17, s29, s35
	s_cselect_b32 s51, s28, s34
	s_ashr_i32 s15, s14, 31
	s_lshl_b64 s[30:31], s[14:15], 19
	s_add_u32 s30, s41, s30
	s_addc_u32 s31, s42, s31
	s_and_b64 s[36:37], s[38:39], exec
	s_cselect_b32 s15, s31, s5
	s_cselect_b32 s52, s30, s4
	s_add_u32 s34, s34, 0x40080
	s_addc_u32 s35, s35, 0
	s_add_u32 s53, s4, 0x100
	v_mov_b32_e32 v0, 0
	s_addc_u32 s54, s5, 0
	s_mov_b32 s55, -2
	v_mov_b32_e32 v1, v0
	v_mov_b32_e32 v2, v0
	v_mov_b32_e32 v3, v0
	v_mov_b32_e32 v4, v0
	v_mov_b32_e32 v5, v0
	v_mov_b32_e32 v6, v0
	v_mov_b32_e32 v7, v0
	v_mov_b32_e32 v16, v0
	v_mov_b32_e32 v17, v0
	v_mov_b32_e32 v18, v0
	v_mov_b32_e32 v19, v0
	v_mov_b32_e32 v20, v0
	v_mov_b32_e32 v21, v0
	v_mov_b32_e32 v22, v0
	v_mov_b32_e32 v23, v0
	v_mov_b32_e32 v32, v0
	v_mov_b32_e32 v33, v0
	v_mov_b32_e32 v34, v0
	v_mov_b32_e32 v35, v0
	v_mov_b32_e32 v36, v0
	v_mov_b32_e32 v37, v0
	v_mov_b32_e32 v38, v0
	v_mov_b32_e32 v39, v0
	v_mov_b32_e32 v48, v0
	v_mov_b32_e32 v49, v0
	v_mov_b32_e32 v50, v0
	v_mov_b32_e32 v51, v0
	v_mov_b32_e32 v52, v0
	v_mov_b32_e32 v53, v0
	v_mov_b32_e32 v54, v0
	v_mov_b32_e32 v55, v0
	v_mov_b32_e32 v8, v0
	v_mov_b32_e32 v9, v0
	v_mov_b32_e32 v10, v0
	v_mov_b32_e32 v11, v0
	v_mov_b32_e32 v12, v0
	v_mov_b32_e32 v13, v0
	v_mov_b32_e32 v14, v0
	v_mov_b32_e32 v15, v0
	v_mov_b32_e32 v24, v0
	v_mov_b32_e32 v25, v0
	v_mov_b32_e32 v26, v0
	v_mov_b32_e32 v27, v0
	v_mov_b32_e32 v28, v0
	v_mov_b32_e32 v29, v0
	v_mov_b32_e32 v30, v0
	v_mov_b32_e32 v31, v0
	v_mov_b32_e32 v40, v0
	v_mov_b32_e32 v41, v0
	v_mov_b32_e32 v42, v0
	v_mov_b32_e32 v43, v0
	v_mov_b32_e32 v44, v0
	v_mov_b32_e32 v45, v0
	v_mov_b32_e32 v46, v0
	v_mov_b32_e32 v47, v0
	v_mov_b32_e32 v56, v0
	v_mov_b32_e32 v57, v0
	v_mov_b32_e32 v58, v0
	v_mov_b32_e32 v59, v0
	v_mov_b32_e32 v60, v0
	v_mov_b32_e32 v61, v0
	v_mov_b32_e32 v62, v0
	v_mov_b32_e32 v63, v0
	v_mov_b32_e32 v64, v0
	v_mov_b32_e32 v65, v0
	v_mov_b32_e32 v66, v0
	v_mov_b32_e32 v67, v0
	v_mov_b32_e32 v68, v0
	v_mov_b32_e32 v69, v0
	v_mov_b32_e32 v70, v0
	v_mov_b32_e32 v71, v0
	v_mov_b32_e32 v80, v0
	v_mov_b32_e32 v81, v0
	v_mov_b32_e32 v82, v0
	v_mov_b32_e32 v83, v0
	v_mov_b32_e32 v84, v0
	v_mov_b32_e32 v85, v0
	v_mov_b32_e32 v86, v0
	v_mov_b32_e32 v87, v0
	v_mov_b32_e32 v96, v0
	v_mov_b32_e32 v97, v0
	v_mov_b32_e32 v98, v0
	v_mov_b32_e32 v99, v0
	v_mov_b32_e32 v100, v0
	v_mov_b32_e32 v101, v0
	v_mov_b32_e32 v102, v0
	v_mov_b32_e32 v103, v0
	v_mov_b32_e32 v112, v0
	v_mov_b32_e32 v113, v0
	v_mov_b32_e32 v114, v0
	v_mov_b32_e32 v115, v0
	v_mov_b32_e32 v116, v0
	v_mov_b32_e32 v117, v0
	v_mov_b32_e32 v118, v0
	v_mov_b32_e32 v119, v0
	v_mov_b32_e32 v72, v0
	v_mov_b32_e32 v73, v0
	v_mov_b32_e32 v74, v0
	v_mov_b32_e32 v75, v0
	v_mov_b32_e32 v76, v0
	v_mov_b32_e32 v77, v0
	v_mov_b32_e32 v78, v0
	v_mov_b32_e32 v79, v0
	v_mov_b32_e32 v88, v0
	v_mov_b32_e32 v89, v0
	v_mov_b32_e32 v90, v0
	v_mov_b32_e32 v91, v0
	v_mov_b32_e32 v92, v0
	v_mov_b32_e32 v93, v0
	v_mov_b32_e32 v94, v0
	v_mov_b32_e32 v95, v0
	v_mov_b32_e32 v104, v0
	v_mov_b32_e32 v105, v0
	v_mov_b32_e32 v106, v0
	v_mov_b32_e32 v107, v0
	v_mov_b32_e32 v108, v0
	v_mov_b32_e32 v109, v0
	v_mov_b32_e32 v110, v0
	v_mov_b32_e32 v111, v0
	v_mov_b32_e32 v120, v0
	v_mov_b32_e32 v121, v0
	v_mov_b32_e32 v122, v0
	v_mov_b32_e32 v123, v0
	v_mov_b32_e32 v124, v0
	v_mov_b32_e32 v125, v0
	v_mov_b32_e32 v126, v0
	v_mov_b32_e32 v127, v0
	s_cmp_eq_u32 s19, 1
	s_cbranch_scc0 .LBB0_937
	s_mov_b32 s19, 0
	s_add_u32 s4, s34, 0xfffc0080
	s_addc_u32 s5, s35, -1
	s_add_i32 s58, 0, 0x10000
	s_cmp_eq_u32 s55, 12
	s_cselect_b32 s37, s17, s5
	s_cselect_b32 s36, s51, s4
	v_add_u32_e32 v138, s58, v141
	s_cselect_b32 s5, s15, s54
	s_cselect_b32 s4, s52, s53
	s_add_i32 s60, 0, 0x14000
	ds_read_b128 v[144:147], v138
	ds_read_b128 v[148:151], v138 offset:1024
	ds_read_b128 v[152:155], v138 offset:2048
	ds_read_b128 v[156:159], v138 offset:3072
	v_add_u32_e32 v138, s60, v141
	ds_read_b128 v[160:163], v138
	ds_read_b128 v[164:167], v138 offset:1024
	ds_read_b128 v[168:171], v138 offset:2048
	ds_read_b128 v[172:175], v138 offset:3072
	v_lshl_add_u64 v[138:139], s[34:35], 0, v[134:135]
	s_add_i32 m0, s27, 0xc000
	ds_read_b128 v[176:179], v143
	ds_read_b128 v[180:183], v143 offset:1024
	ds_read_b128 v[184:187], v143 offset:2048
	ds_read_b128 v[188:191], v143 offset:3072
	ds_read_b128 v[208:211], v143 offset:4096
	ds_read_b128 v[212:215], v143 offset:5120
	ds_read_b128 v[216:219], v143 offset:6144
	ds_read_b128 v[220:223], v143 offset:7168
	global_load_lds_dwordx4 v[138:139], off
	v_lshl_add_u64 v[138:139], s[34:35], 0, v[136:137]
	s_add_i32 m0, s27, 0xe000
	s_nop 0
	global_load_lds_dwordx4 v[138:139], off
	s_waitcnt vmcnt(16)
	s_waitcnt lgkmcnt(0)
	s_barrier
	s_setprio 1
	s_waitcnt lgkmcnt(0)
	v_mfma_f32_16x16x32_bf16 v[124:127], v[144:147], v[176:179], v[124:127]
	v_mfma_f32_16x16x32_bf16 v[120:123], v[152:155], v[176:179], v[120:123]
	v_mfma_f32_16x16x32_bf16 v[108:111], v[144:147], v[184:187], v[108:111]
	v_mfma_f32_16x16x32_bf16 v[104:107], v[152:155], v[184:187], v[104:107]
	v_mfma_f32_16x16x32_bf16 v[92:95], v[144:147], v[208:211], v[92:95]
	v_mfma_f32_16x16x32_bf16 v[88:91], v[152:155], v[208:211], v[88:91]
	v_mfma_f32_16x16x32_bf16 v[76:79], v[144:147], v[216:219], v[76:79]
	v_mfma_f32_16x16x32_bf16 v[72:75], v[152:155], v[216:219], v[72:75]
	v_mfma_f32_16x16x32_bf16 v[124:127], v[148:151], v[180:183], v[124:127]
	v_mfma_f32_16x16x32_bf16 v[120:123], v[156:159], v[180:183], v[120:123]
	v_mfma_f32_16x16x32_bf16 v[108:111], v[148:151], v[188:191], v[108:111]
	v_mfma_f32_16x16x32_bf16 v[104:107], v[156:159], v[188:191], v[104:107]
	v_mfma_f32_16x16x32_bf16 v[92:95], v[148:151], v[212:215], v[92:95]
	v_mfma_f32_16x16x32_bf16 v[88:91], v[156:159], v[212:215], v[88:91]
	v_mfma_f32_16x16x32_bf16 v[76:79], v[148:151], v[220:223], v[76:79]
	v_mfma_f32_16x16x32_bf16 v[72:75], v[156:159], v[220:223], v[72:75]
	s_setprio 0
	s_setprio 1
	v_mfma_f32_16x16x32_bf16 v[116:119], v[160:163], v[176:179], v[116:119]
	v_mfma_f32_16x16x32_bf16 v[112:115], v[168:171], v[176:179], v[112:115]
	v_mfma_f32_16x16x32_bf16 v[100:103], v[160:163], v[184:187], v[100:103]
	v_mfma_f32_16x16x32_bf16 v[96:99], v[168:171], v[184:187], v[96:99]
	v_mfma_f32_16x16x32_bf16 v[84:87], v[160:163], v[208:211], v[84:87]
	v_mfma_f32_16x16x32_bf16 v[80:83], v[168:171], v[208:211], v[80:83]
	v_mfma_f32_16x16x32_bf16 v[68:71], v[160:163], v[216:219], v[68:71]
	v_mfma_f32_16x16x32_bf16 v[64:67], v[168:171], v[216:219], v[64:67]
	v_mfma_f32_16x16x32_bf16 v[116:119], v[164:167], v[180:183], v[116:119]
	v_mfma_f32_16x16x32_bf16 v[112:115], v[172:175], v[180:183], v[112:115]
	v_mfma_f32_16x16x32_bf16 v[100:103], v[164:167], v[188:191], v[100:103]
	v_mfma_f32_16x16x32_bf16 v[96:99], v[172:175], v[188:191], v[96:99]
	v_mfma_f32_16x16x32_bf16 v[84:87], v[164:167], v[212:215], v[84:87]
	v_mfma_f32_16x16x32_bf16 v[80:83], v[172:175], v[212:215], v[80:83]
	v_mfma_f32_16x16x32_bf16 v[68:71], v[164:167], v[220:223], v[68:71]
	v_mfma_f32_16x16x32_bf16 v[64:67], v[172:175], v[220:223], v[64:67]
	s_setprio 0
	s_barrier
	s_add_i32 s58, s58, s44
	v_lshl_add_u64 v[138:139], s[4:5], 0, v[192:193]
	s_mov_b32 m0, s58
	ds_read_b128 v[176:179], v143 offset:16384
	ds_read_b128 v[180:183], v143 offset:17408
	ds_read_b128 v[184:187], v143 offset:18432
	ds_read_b128 v[188:191], v143 offset:19456
	ds_read_b128 v[208:211], v143 offset:20480
	ds_read_b128 v[212:215], v143 offset:21504
	ds_read_b128 v[216:219], v143 offset:22528
	ds_read_b128 v[220:223], v143 offset:23552
	global_load_lds_dwordx4 v[138:139], off
	s_add_i32 m0, s58, 0x2000
	s_add_u32 s58, s4, 0x40000
	v_lshl_add_u64 v[224:225], s[4:5], 0, v[128:129]
	s_addc_u32 s59, s5, 0
	s_add_i32 s60, s60, s44
	global_load_lds_dwordx4 v[224:225], off
	v_lshl_add_u64 v[226:227], s[58:59], 0, v[192:193]
	s_mov_b32 m0, s60
	v_lshl_add_u64 v[228:229], s[36:37], 0, v[130:131]
	global_load_lds_dwordx4 v[226:227], off
	v_lshl_add_u64 v[226:227], s[58:59], 0, v[128:129]
	s_add_i32 m0, s60, 0x2000
	s_nop 0
	global_load_lds_dwordx4 v[226:227], off
	v_lshl_add_u64 v[226:227], s[36:37], 0, v[132:133]
	s_mov_b32 m0, s27
	s_nop 0
	global_load_lds_dwordx4 v[226:227], off
	s_mov_b32 m0, s45
	s_nop 0
	global_load_lds_dwordx4 v[228:229], off
	s_waitcnt vmcnt(16)
	s_branch .Lpeel_mid_up2

.Lpeel_mid_up2:
	s_waitcnt lgkmcnt(0)
	s_barrier
	s_setprio 1
	s_waitcnt lgkmcnt(0)
	v_mfma_f32_16x16x32_bf16 v[60:63], v[144:147], v[176:179], v[60:63]
	v_mfma_f32_16x16x32_bf16 v[56:59], v[152:155], v[176:179], v[56:59]
	v_mfma_f32_16x16x32_bf16 v[44:47], v[144:147], v[184:187], v[44:47]
	v_mfma_f32_16x16x32_bf16 v[40:43], v[152:155], v[184:187], v[40:43]
	v_mfma_f32_16x16x32_bf16 v[28:31], v[144:147], v[208:211], v[28:31]
	v_mfma_f32_16x16x32_bf16 v[24:27], v[152:155], v[208:211], v[24:27]
	v_mfma_f32_16x16x32_bf16 v[12:15], v[144:147], v[216:219], v[12:15]
	v_mfma_f32_16x16x32_bf16 v[8:11], v[152:155], v[216:219], v[8:11]
	v_mfma_f32_16x16x32_bf16 v[60:63], v[148:151], v[180:183], v[60:63]
	v_mfma_f32_16x16x32_bf16 v[56:59], v[156:159], v[180:183], v[56:59]
	v_mfma_f32_16x16x32_bf16 v[44:47], v[148:151], v[188:191], v[44:47]
	v_mfma_f32_16x16x32_bf16 v[40:43], v[156:159], v[188:191], v[40:43]
	v_mfma_f32_16x16x32_bf16 v[28:31], v[148:151], v[212:215], v[28:31]
	v_mfma_f32_16x16x32_bf16 v[24:27], v[156:159], v[212:215], v[24:27]
	v_mfma_f32_16x16x32_bf16 v[12:15], v[148:151], v[220:223], v[12:15]
	v_mfma_f32_16x16x32_bf16 v[8:11], v[156:159], v[220:223], v[8:11]
	s_setprio 0
	s_setprio 1
	v_mfma_f32_16x16x32_bf16 v[52:55], v[160:163], v[176:179], v[52:55]
	v_mfma_f32_16x16x32_bf16 v[48:51], v[168:171], v[176:179], v[48:51]
	v_mfma_f32_16x16x32_bf16 v[36:39], v[160:163], v[184:187], v[36:39]
	v_mfma_f32_16x16x32_bf16 v[32:35], v[168:171], v[184:187], v[32:35]
	v_mfma_f32_16x16x32_bf16 v[20:23], v[160:163], v[208:211], v[20:23]
	v_mfma_f32_16x16x32_bf16 v[16:19], v[168:171], v[208:211], v[16:19]
	v_mfma_f32_16x16x32_bf16 v[4:7], v[160:163], v[216:219], v[4:7]
	v_mfma_f32_16x16x32_bf16 v[0:3], v[168:171], v[216:219], v[0:3]
	v_mfma_f32_16x16x32_bf16 v[52:55], v[164:167], v[180:183], v[52:55]
	v_mfma_f32_16x16x32_bf16 v[48:51], v[172:175], v[180:183], v[48:51]
	v_mfma_f32_16x16x32_bf16 v[36:39], v[164:167], v[188:191], v[36:39]
	v_mfma_f32_16x16x32_bf16 v[32:35], v[172:175], v[188:191], v[32:35]
	v_mfma_f32_16x16x32_bf16 v[20:23], v[164:167], v[212:215], v[20:23]
	v_mfma_f32_16x16x32_bf16 v[16:19], v[172:175], v[212:215], v[16:19]
	v_mfma_f32_16x16x32_bf16 v[4:7], v[164:167], v[220:223], v[4:7]
	v_mfma_f32_16x16x32_bf16 v[0:3], v[172:175], v[220:223], v[0:3]
	s_setprio 0
	s_barrier
	s_add_i32 s58, 0, 0x18000
	s_add_i32 s59, 0, 0x1c000
	v_add_u32_e32 v156, s58, v141
	v_add_u32_e32 v172, s59, v141
	ds_read_b128 v[144:147], v156
	ds_read_b128 v[148:151], v156 offset:1024
	ds_read_b128 v[152:155], v156 offset:2048
	ds_read_b128 v[156:159], v156 offset:3072
	ds_read_b128 v[160:163], v172
	ds_read_b128 v[164:167], v172 offset:1024
	ds_read_b128 v[168:171], v172 offset:2048
	ds_read_b128 v[172:175], v172 offset:3072
	s_add_u32 s36, s36, 0x40000
	s_addc_u32 s37, s37, 0
	s_mov_b32 m0, s46
	v_lshl_add_u64 v[230:231], s[36:37], 0, v[132:133]
	ds_read_b128 v[176:179], v143 offset:32768
	ds_read_b128 v[180:183], v143 offset:33792
	ds_read_b128 v[184:187], v143 offset:34816
	ds_read_b128 v[188:191], v143 offset:35840
	ds_read_b128 v[208:211], v143 offset:36864
	ds_read_b128 v[212:215], v143 offset:37888
	ds_read_b128 v[216:219], v143 offset:38912
	ds_read_b128 v[220:223], v143 offset:39936
	global_load_lds_dwordx4 v[230:231], off
	v_lshl_add_u64 v[230:231], s[36:37], 0, v[130:131]
	s_mov_b32 m0, s47
	s_nop 0
	global_load_lds_dwordx4 v[230:231], off
	s_waitcnt vmcnt(8)
	s_waitcnt lgkmcnt(0)
	s_barrier
	s_setprio 1
	s_waitcnt lgkmcnt(0)
	v_mfma_f32_16x16x32_bf16 v[124:127], v[144:147], v[176:179], v[124:127]
	v_mfma_f32_16x16x32_bf16 v[120:123], v[152:155], v[176:179], v[120:123]
	v_mfma_f32_16x16x32_bf16 v[108:111], v[144:147], v[184:187], v[108:111]
	v_mfma_f32_16x16x32_bf16 v[104:107], v[152:155], v[184:187], v[104:107]
	v_mfma_f32_16x16x32_bf16 v[92:95], v[144:147], v[208:211], v[92:95]
	v_mfma_f32_16x16x32_bf16 v[88:91], v[152:155], v[208:211], v[88:91]
	v_mfma_f32_16x16x32_bf16 v[76:79], v[144:147], v[216:219], v[76:79]
	v_mfma_f32_16x16x32_bf16 v[72:75], v[152:155], v[216:219], v[72:75]
	v_mfma_f32_16x16x32_bf16 v[124:127], v[148:151], v[180:183], v[124:127]
	v_mfma_f32_16x16x32_bf16 v[120:123], v[156:159], v[180:183], v[120:123]
	v_mfma_f32_16x16x32_bf16 v[108:111], v[148:151], v[188:191], v[108:111]
	v_mfma_f32_16x16x32_bf16 v[104:107], v[156:159], v[188:191], v[104:107]
	v_mfma_f32_16x16x32_bf16 v[92:95], v[148:151], v[212:215], v[92:95]
	v_mfma_f32_16x16x32_bf16 v[88:91], v[156:159], v[212:215], v[88:91]
	v_mfma_f32_16x16x32_bf16 v[76:79], v[148:151], v[220:223], v[76:79]
	v_mfma_f32_16x16x32_bf16 v[72:75], v[156:159], v[220:223], v[72:75]
	s_setprio 0
	s_setprio 1
	v_mfma_f32_16x16x32_bf16 v[116:119], v[160:163], v[176:179], v[116:119]
	v_mfma_f32_16x16x32_bf16 v[112:115], v[168:171], v[176:179], v[112:115]
	v_mfma_f32_16x16x32_bf16 v[100:103], v[160:163], v[184:187], v[100:103]
	v_mfma_f32_16x16x32_bf16 v[96:99], v[168:171], v[184:187], v[96:99]
	v_mfma_f32_16x16x32_bf16 v[84:87], v[160:163], v[208:211], v[84:87]
	v_mfma_f32_16x16x32_bf16 v[80:83], v[168:171], v[208:211], v[80:83]
	v_mfma_f32_16x16x32_bf16 v[68:71], v[160:163], v[216:219], v[68:71]
	v_mfma_f32_16x16x32_bf16 v[64:67], v[168:171], v[216:219], v[64:67]
	v_mfma_f32_16x16x32_bf16 v[116:119], v[164:167], v[180:183], v[116:119]
	v_mfma_f32_16x16x32_bf16 v[112:115], v[172:175], v[180:183], v[112:115]
	v_mfma_f32_16x16x32_bf16 v[100:103], v[164:167], v[188:191], v[100:103]
	v_mfma_f32_16x16x32_bf16 v[96:99], v[172:175], v[188:191], v[96:99]
	v_mfma_f32_16x16x32_bf16 v[84:87], v[164:167], v[212:215], v[84:87]
	v_mfma_f32_16x16x32_bf16 v[80:83], v[172:175], v[212:215], v[80:83]
	v_mfma_f32_16x16x32_bf16 v[68:71], v[164:167], v[220:223], v[68:71]
	v_mfma_f32_16x16x32_bf16 v[64:67], v[172:175], v[220:223], v[64:67]
	s_setprio 0
	s_barrier
	s_add_i32 s36, s58, s44
	v_lshl_add_u64 v[138:139], v[138:139], 0, s[8:9]
	s_mov_b32 m0, s36
	ds_read_b128 v[176:179], v143 offset:49152
	ds_read_b128 v[180:183], v143 offset:50176
	ds_read_b128 v[184:187], v143 offset:51200
	ds_read_b128 v[188:191], v143 offset:52224
	ds_read_b128 v[208:211], v143 offset:53248
	ds_read_b128 v[212:215], v143 offset:54272
	ds_read_b128 v[216:219], v143 offset:55296
	ds_read_b128 v[220:223], v143 offset:56320
	global_load_lds_dwordx4 v[138:139], off
	s_add_i32 m0, s36, 0x2000
	s_add_u32 s4, s4, 0x40080
	v_lshl_add_u64 v[138:139], v[224:225], 0, s[8:9]
	s_addc_u32 s5, s5, 0
	s_add_i32 s36, s59, s44
	global_load_lds_dwordx4 v[138:139], off
	v_lshl_add_u64 v[138:139], s[4:5], 0, v[192:193]
	s_mov_b32 m0, s36
	s_nop 0
	global_load_lds_dwordx4 v[138:139], off
	v_lshl_add_u64 v[138:139], s[4:5], 0, v[128:129]
	s_add_i32 m0, s36, 0x2000
	s_nop 0
	global_load_lds_dwordx4 v[138:139], off
	v_lshl_add_u64 v[138:139], v[226:227], 0, s[8:9]
	s_mov_b32 m0, s2
	s_nop 0
	global_load_lds_dwordx4 v[138:139], off
	v_lshl_add_u64 v[138:139], v[228:229], 0, s[8:9]
	s_mov_b32 m0, s48
	s_nop 0
	global_load_lds_dwordx4 v[138:139], off
	s_waitcnt vmcnt(8)
	s_waitcnt lgkmcnt(0)
	s_barrier
	s_setprio 1
	s_waitcnt lgkmcnt(0)
	v_mfma_f32_16x16x32_bf16 v[60:63], v[144:147], v[176:179], v[60:63]
	v_mfma_f32_16x16x32_bf16 v[56:59], v[152:155], v[176:179], v[56:59]
	v_mfma_f32_16x16x32_bf16 v[44:47], v[144:147], v[184:187], v[44:47]
	v_mfma_f32_16x16x32_bf16 v[40:43], v[152:155], v[184:187], v[40:43]
	v_mfma_f32_16x16x32_bf16 v[28:31], v[144:147], v[208:211], v[28:31]
	v_mfma_f32_16x16x32_bf16 v[24:27], v[152:155], v[208:211], v[24:27]
	v_mfma_f32_16x16x32_bf16 v[12:15], v[144:147], v[216:219], v[12:15]
	v_mfma_f32_16x16x32_bf16 v[8:11], v[152:155], v[216:219], v[8:11]
	v_mfma_f32_16x16x32_bf16 v[60:63], v[148:151], v[180:183], v[60:63]
	v_mfma_f32_16x16x32_bf16 v[56:59], v[156:159], v[180:183], v[56:59]
	v_mfma_f32_16x16x32_bf16 v[44:47], v[148:151], v[188:191], v[44:47]
	v_mfma_f32_16x16x32_bf16 v[40:43], v[156:159], v[188:191], v[40:43]
	v_mfma_f32_16x16x32_bf16 v[28:31], v[148:151], v[212:215], v[28:31]
	v_mfma_f32_16x16x32_bf16 v[24:27], v[156:159], v[212:215], v[24:27]
	v_mfma_f32_16x16x32_bf16 v[12:15], v[148:151], v[220:223], v[12:15]
	v_mfma_f32_16x16x32_bf16 v[8:11], v[156:159], v[220:223], v[8:11]
	s_setprio 0
	s_setprio 1
	v_mfma_f32_16x16x32_bf16 v[52:55], v[160:163], v[176:179], v[52:55]
	v_mfma_f32_16x16x32_bf16 v[48:51], v[168:171], v[176:179], v[48:51]
	v_mfma_f32_16x16x32_bf16 v[36:39], v[160:163], v[184:187], v[36:39]
	v_mfma_f32_16x16x32_bf16 v[32:35], v[168:171], v[184:187], v[32:35]
	v_mfma_f32_16x16x32_bf16 v[20:23], v[160:163], v[208:211], v[20:23]
	v_mfma_f32_16x16x32_bf16 v[16:19], v[168:171], v[208:211], v[16:19]
	v_mfma_f32_16x16x32_bf16 v[4:7], v[160:163], v[216:219], v[4:7]
	v_mfma_f32_16x16x32_bf16 v[0:3], v[168:171], v[216:219], v[0:3]
	v_mfma_f32_16x16x32_bf16 v[52:55], v[164:167], v[180:183], v[52:55]
	v_mfma_f32_16x16x32_bf16 v[48:51], v[172:175], v[180:183], v[48:51]
	v_mfma_f32_16x16x32_bf16 v[36:39], v[164:167], v[188:191], v[36:39]
	v_mfma_f32_16x16x32_bf16 v[32:35], v[172:175], v[188:191], v[32:35]
	v_mfma_f32_16x16x32_bf16 v[20:23], v[164:167], v[212:215], v[20:23]
	v_mfma_f32_16x16x32_bf16 v[16:19], v[172:175], v[212:215], v[16:19]
	v_mfma_f32_16x16x32_bf16 v[4:7], v[164:167], v[220:223], v[4:7]
	v_mfma_f32_16x16x32_bf16 v[0:3], v[172:175], v[220:223], v[0:3]
	s_setprio 0
	s_barrier
	s_add_i32 s55, s55, 2
	s_add_u32 s34, s34, 0x100
	s_addc_u32 s35, s35, 0
	s_add_u32 s53, s53, 0x100
	s_addc_u32 s54, s54, 0
	s_cmp_gt_u32 s55, 13
	s_cbranch_scc0 .LBB0_937
	s_and_b64 vcc, exec, s[12:13]
	s_cbranch_vccz .LBB0_940
	s_barrier
.LBB0_940:
	v_mul_f32_e32 v138, 0xbfb8aa3b, v124
	v_exp_f32_e32 v138, v138
	v_mul_f32_e32 v139, 0xbfb8aa3b, v125
	v_exp_f32_e32 v139, v139
	v_mul_f32_e32 v145, 0xbfb8aa3b, v126
	v_add_f32_e32 v138, 1.0, v138
	v_rcp_f32_e32 v148, v138
	v_add_f32_e32 v138, 1.0, v139
	v_rcp_f32_e32 v149, v138
	v_exp_f32_e32 v145, v145
	v_lshl_or_b32 v146, s50, 7, v142
	v_lshl_add_u32 v144, s26, 8, v140
	v_pk_mul_f32 v[124:125], v[124:125], v[148:149]
	v_mul_f32_e32 v148, 0xbfb8aa3b, v127
	v_exp_f32_e32 v148, v148
	v_pk_mul_f32 v[116:117], v[124:125], v[116:117]
	v_add_f32_e32 v124, 1.0, v145
	v_mul_f32_e32 v145, 0xbfb8aa3b, v120
	v_add_f32_e32 v125, 1.0, v148
	v_rcp_f32_e32 v124, v124
	v_rcp_f32_e32 v125, v125
	v_exp_f32_e32 v145, v145
	v_mul_f32_e32 v148, 0xbfb8aa3b, v121
	v_exp_f32_e32 v148, v148
	v_pk_mul_f32 v[124:125], v[126:127], v[124:125]
	v_add_f32_e32 v126, 1.0, v145
	v_mul_f32_e32 v145, 0xbfb8aa3b, v122
	v_add_f32_e32 v127, 1.0, v148
	v_exp_f32_e32 v145, v145
	v_mul_f32_e32 v148, 0xbfb8aa3b, v123
	v_exp_f32_e32 v149, v148
	v_rcp_f32_e32 v126, v126
	v_add_f32_e32 v145, 1.0, v145
	v_rcp_f32_e32 v127, v127
	v_rcp_f32_e32 v148, v145
	v_add_f32_e32 v145, 1.0, v149
	v_rcp_f32_e32 v149, v145
	v_pk_mul_f32 v[120:121], v[120:121], v[126:127]
	v_pk_mul_f32 v[118:119], v[124:125], v[118:119]
	v_pk_mul_f32 v[120:121], v[120:121], v[112:113]
	v_pk_mul_f32 v[112:113], v[122:123], v[148:149]
	v_ashrrev_i32_e32 v147, 31, v146
	v_pk_mul_f32 v[122:123], v[112:113], v[114:115]
	v_cvt_pk_bf16_f32 v115, v118, v119
	v_mul_f32_e32 v118, 0xbfb8aa3b, v108
	v_mul_f32_e32 v119, 0xbfb8aa3b, v109
	v_exp_f32_e32 v118, v118
	v_exp_f32_e32 v119, v119
	v_mov_b64_e32 v[138:139], s[10:11]
	v_mad_i64_i32 v[150:151], s[4:5], v144, s33, v[138:139]
	v_lshlrev_b64 v[112:113], 1, v[146:147]
	v_lshl_add_u64 v[124:125], v[150:151], 0, v[112:113]
	v_cvt_pk_bf16_f32 v114, v116, v117
	v_cvt_pk_bf16_f32 v116, v120, v121
	v_cvt_pk_bf16_f32 v117, v122, v123
	global_store_dwordx4 v[124:125], v[114:117], off
	s_andn2_b64 vcc, exec, s[38:39]
	s_nop 0
	v_add_f32_e32 v114, 1.0, v118
	v_add_f32_e32 v115, 1.0, v119
	v_rcp_f32_e32 v114, v114
	v_rcp_f32_e32 v115, v115
	v_or_b32_e32 v116, 16, v144
	v_mad_i64_i32 v[116:117], s[4:5], v116, s33, v[138:139]
	v_pk_mul_f32 v[108:109], v[108:109], v[114:115]
	v_mul_f32_e32 v114, 0xbfb8aa3b, v110
	v_mul_f32_e32 v115, 0xbfb8aa3b, v111
	v_exp_f32_e32 v114, v114
	v_exp_f32_e32 v115, v115
	v_pk_mul_f32 v[100:101], v[108:109], v[100:101]
	v_add_f32_e32 v108, 1.0, v114
	v_add_f32_e32 v109, 1.0, v115
	v_mul_f32_e32 v114, 0xbfb8aa3b, v104
	v_mul_f32_e32 v115, 0xbfb8aa3b, v105
	v_rcp_f32_e32 v108, v108
	v_rcp_f32_e32 v109, v109
	v_exp_f32_e32 v114, v114
	v_exp_f32_e32 v115, v115
	v_pk_mul_f32 v[108:109], v[110:111], v[108:109]
	v_add_f32_e32 v110, 1.0, v114
	v_add_f32_e32 v111, 1.0, v115
	v_mul_f32_e32 v114, 0xbfb8aa3b, v106
	v_mul_f32_e32 v115, 0xbfb8aa3b, v107
	v_exp_f32_e32 v114, v114
	v_exp_f32_e32 v115, v115
	v_rcp_f32_e32 v110, v110
	v_rcp_f32_e32 v111, v111
	v_add_f32_e32 v114, 1.0, v114
	v_add_f32_e32 v115, 1.0, v115
	v_rcp_f32_e32 v114, v114
	v_rcp_f32_e32 v115, v115
	v_pk_mul_f32 v[104:105], v[104:105], v[110:111]
	v_pk_mul_f32 v[102:103], v[108:109], v[102:103]
	v_pk_mul_f32 v[104:105], v[104:105], v[96:97]
	v_pk_mul_f32 v[96:97], v[106:107], v[114:115]
	v_lshl_add_u64 v[108:109], v[116:117], 0, v[112:113]
	v_pk_mul_f32 v[106:107], v[96:97], v[98:99]
	v_cvt_pk_bf16_f32 v96, v100, v101
	v_mul_f32_e32 v100, 0xbfb8aa3b, v92
	v_mul_f32_e32 v101, 0xbfb8aa3b, v93
	v_exp_f32_e32 v100, v100
	v_exp_f32_e32 v101, v101
	v_cvt_pk_bf16_f32 v97, v102, v103
	v_cvt_pk_bf16_f32 v98, v104, v105
	v_cvt_pk_bf16_f32 v99, v106, v107
	global_store_dwordx4 v[108:109], v[96:99], off
	s_nop 1
	v_add_f32_e32 v96, 1.0, v100
	v_add_f32_e32 v97, 1.0, v101
	v_rcp_f32_e32 v96, v96
	v_rcp_f32_e32 v97, v97
	v_or_b32_e32 v98, 32, v144
	v_mad_i64_i32 v[98:99], s[4:5], v98, s33, v[138:139]
	v_pk_mul_f32 v[92:93], v[92:93], v[96:97]
	v_mul_f32_e32 v96, 0xbfb8aa3b, v94
	v_mul_f32_e32 v97, 0xbfb8aa3b, v95
	v_exp_f32_e32 v96, v96
	v_exp_f32_e32 v97, v97
	v_pk_mul_f32 v[84:85], v[92:93], v[84:85]
	v_add_f32_e32 v92, 1.0, v96
	v_add_f32_e32 v93, 1.0, v97
	v_mul_f32_e32 v96, 0xbfb8aa3b, v88
	v_mul_f32_e32 v97, 0xbfb8aa3b, v89
	v_rcp_f32_e32 v92, v92
	v_rcp_f32_e32 v93, v93
	v_exp_f32_e32 v96, v96
	v_exp_f32_e32 v97, v97
	v_pk_mul_f32 v[92:93], v[94:95], v[92:93]
	v_add_f32_e32 v94, 1.0, v96
	v_add_f32_e32 v95, 1.0, v97
	v_mul_f32_e32 v96, 0xbfb8aa3b, v90
	v_mul_f32_e32 v97, 0xbfb8aa3b, v91
	v_exp_f32_e32 v96, v96
	v_exp_f32_e32 v97, v97
	v_rcp_f32_e32 v94, v94
	v_rcp_f32_e32 v95, v95
	v_add_f32_e32 v96, 1.0, v96
	v_add_f32_e32 v97, 1.0, v97
	v_rcp_f32_e32 v96, v96
	v_rcp_f32_e32 v97, v97
	v_pk_mul_f32 v[88:89], v[88:89], v[94:95]
	v_pk_mul_f32 v[86:87], v[92:93], v[86:87]
	v_pk_mul_f32 v[88:89], v[88:89], v[80:81]
	v_pk_mul_f32 v[80:81], v[90:91], v[96:97]
	v_lshl_add_u64 v[92:93], v[98:99], 0, v[112:113]
	v_pk_mul_f32 v[90:91], v[80:81], v[82:83]
	v_cvt_pk_bf16_f32 v80, v84, v85
	v_mul_f32_e32 v84, 0xbfb8aa3b, v76
	v_mul_f32_e32 v85, 0xbfb8aa3b, v77
	v_exp_f32_e32 v84, v84
	v_exp_f32_e32 v85, v85
	v_cvt_pk_bf16_f32 v81, v86, v87
	v_cvt_pk_bf16_f32 v82, v88, v89
	v_cvt_pk_bf16_f32 v83, v90, v91
	global_store_dwordx4 v[92:93], v[80:83], off
	s_nop 1
	v_add_f32_e32 v80, 1.0, v84
	v_add_f32_e32 v81, 1.0, v85
	v_rcp_f32_e32 v80, v80
	v_rcp_f32_e32 v81, v81
	v_or_b32_e32 v82, 48, v144
	v_mad_i64_i32 v[82:83], s[4:5], v82, s33, v[138:139]
	v_pk_mul_f32 v[76:77], v[76:77], v[80:81]
	v_mul_f32_e32 v80, 0xbfb8aa3b, v78
	v_mul_f32_e32 v81, 0xbfb8aa3b, v79
	v_exp_f32_e32 v80, v80
	v_exp_f32_e32 v81, v81
	v_pk_mul_f32 v[68:69], v[76:77], v[68:69]
	v_add_f32_e32 v76, 1.0, v80
	v_add_f32_e32 v77, 1.0, v81
	v_mul_f32_e32 v80, 0xbfb8aa3b, v72
	v_mul_f32_e32 v81, 0xbfb8aa3b, v73
	v_rcp_f32_e32 v76, v76
	v_rcp_f32_e32 v77, v77
	v_exp_f32_e32 v80, v80
	v_exp_f32_e32 v81, v81
	v_pk_mul_f32 v[76:77], v[78:79], v[76:77]
	v_add_f32_e32 v78, 1.0, v80
	v_add_f32_e32 v79, 1.0, v81
	v_mul_f32_e32 v80, 0xbfb8aa3b, v74
	v_mul_f32_e32 v81, 0xbfb8aa3b, v75
	v_exp_f32_e32 v80, v80
	v_exp_f32_e32 v81, v81
	v_rcp_f32_e32 v78, v78
	v_rcp_f32_e32 v79, v79
	v_add_f32_e32 v80, 1.0, v80
	v_add_f32_e32 v81, 1.0, v81
	v_rcp_f32_e32 v80, v80
	v_rcp_f32_e32 v81, v81
	v_pk_mul_f32 v[72:73], v[72:73], v[78:79]
	v_pk_mul_f32 v[70:71], v[76:77], v[70:71]
	v_pk_mul_f32 v[72:73], v[72:73], v[64:65]
	v_pk_mul_f32 v[64:65], v[74:75], v[80:81]
	v_lshl_add_u64 v[76:77], v[82:83], 0, v[112:113]
	v_pk_mul_f32 v[74:75], v[64:65], v[66:67]
	v_cvt_pk_bf16_f32 v64, v68, v69
	v_mul_f32_e32 v68, 0xbfb8aa3b, v60
	v_mul_f32_e32 v69, 0xbfb8aa3b, v61
	v_exp_f32_e32 v68, v68
	v_exp_f32_e32 v69, v69
	v_cvt_pk_bf16_f32 v65, v70, v71
	v_cvt_pk_bf16_f32 v66, v72, v73
	v_cvt_pk_bf16_f32 v67, v74, v75
	global_store_dwordx4 v[76:77], v[64:67], off
	s_nop 1
	v_add_f32_e32 v64, 1.0, v68
	v_add_f32_e32 v65, 1.0, v69
	v_rcp_f32_e32 v64, v64
	v_rcp_f32_e32 v65, v65
	v_add_u32_e32 v66, 0x80, v144
	v_mad_i64_i32 v[66:67], s[4:5], v66, s33, v[138:139]
	v_pk_mul_f32 v[60:61], v[60:61], v[64:65]
	v_mul_f32_e32 v64, 0xbfb8aa3b, v62
	v_mul_f32_e32 v65, 0xbfb8aa3b, v63
	v_exp_f32_e32 v64, v64
	v_exp_f32_e32 v65, v65
	v_pk_mul_f32 v[52:53], v[60:61], v[52:53]
	v_add_f32_e32 v60, 1.0, v64
	v_add_f32_e32 v61, 1.0, v65
	v_mul_f32_e32 v64, 0xbfb8aa3b, v56
	v_mul_f32_e32 v65, 0xbfb8aa3b, v57
	v_rcp_f32_e32 v60, v60
	v_rcp_f32_e32 v61, v61
	v_exp_f32_e32 v64, v64
	v_exp_f32_e32 v65, v65
	v_pk_mul_f32 v[60:61], v[62:63], v[60:61]
	v_add_f32_e32 v62, 1.0, v64
	v_add_f32_e32 v63, 1.0, v65
	v_mul_f32_e32 v64, 0xbfb8aa3b, v58
	v_mul_f32_e32 v65, 0xbfb8aa3b, v59
	v_exp_f32_e32 v64, v64
	v_exp_f32_e32 v65, v65
	v_rcp_f32_e32 v62, v62
	v_rcp_f32_e32 v63, v63
	v_add_f32_e32 v64, 1.0, v64
	v_add_f32_e32 v65, 1.0, v65
	v_rcp_f32_e32 v64, v64
	v_rcp_f32_e32 v65, v65
	v_pk_mul_f32 v[56:57], v[56:57], v[62:63]
	v_pk_mul_f32 v[54:55], v[60:61], v[54:55]
	v_pk_mul_f32 v[56:57], v[56:57], v[48:49]
	v_pk_mul_f32 v[48:49], v[58:59], v[64:65]
	v_lshl_add_u64 v[60:61], v[66:67], 0, v[112:113]
	v_pk_mul_f32 v[58:59], v[48:49], v[50:51]
	v_cvt_pk_bf16_f32 v48, v52, v53
	v_mul_f32_e32 v52, 0xbfb8aa3b, v44
	v_mul_f32_e32 v53, 0xbfb8aa3b, v45
	v_exp_f32_e32 v52, v52
	v_exp_f32_e32 v53, v53
	v_cvt_pk_bf16_f32 v49, v54, v55
	v_cvt_pk_bf16_f32 v50, v56, v57
	v_cvt_pk_bf16_f32 v51, v58, v59
	global_store_dwordx4 v[60:61], v[48:51], off
	s_nop 1
	v_add_f32_e32 v48, 1.0, v52
	v_add_f32_e32 v49, 1.0, v53
	v_rcp_f32_e32 v48, v48
	v_rcp_f32_e32 v49, v49
	v_add_u32_e32 v50, 0x90, v144
	v_mad_i64_i32 v[50:51], s[4:5], v50, s33, v[138:139]
	v_pk_mul_f32 v[44:45], v[44:45], v[48:49]
	v_mul_f32_e32 v48, 0xbfb8aa3b, v46
	v_mul_f32_e32 v49, 0xbfb8aa3b, v47
	v_exp_f32_e32 v48, v48
	v_exp_f32_e32 v49, v49
	v_pk_mul_f32 v[36:37], v[44:45], v[36:37]
	v_add_f32_e32 v44, 1.0, v48
	v_add_f32_e32 v45, 1.0, v49
	v_mul_f32_e32 v48, 0xbfb8aa3b, v40
	v_mul_f32_e32 v49, 0xbfb8aa3b, v41
	v_rcp_f32_e32 v44, v44
	v_rcp_f32_e32 v45, v45
	v_exp_f32_e32 v48, v48
	v_exp_f32_e32 v49, v49
	v_pk_mul_f32 v[44:45], v[46:47], v[44:45]
	v_add_f32_e32 v46, 1.0, v48
	v_add_f32_e32 v47, 1.0, v49
	v_mul_f32_e32 v48, 0xbfb8aa3b, v42
	v_mul_f32_e32 v49, 0xbfb8aa3b, v43
	v_exp_f32_e32 v48, v48
	v_exp_f32_e32 v49, v49
	v_rcp_f32_e32 v46, v46
	v_rcp_f32_e32 v47, v47
	v_add_f32_e32 v48, 1.0, v48
	v_add_f32_e32 v49, 1.0, v49
	v_rcp_f32_e32 v48, v48
	v_rcp_f32_e32 v49, v49
	v_pk_mul_f32 v[40:41], v[40:41], v[46:47]
	v_pk_mul_f32 v[38:39], v[44:45], v[38:39]
	v_pk_mul_f32 v[40:41], v[40:41], v[32:33]
	v_pk_mul_f32 v[32:33], v[42:43], v[48:49]
	v_lshl_add_u64 v[44:45], v[50:51], 0, v[112:113]
	v_pk_mul_f32 v[42:43], v[32:33], v[34:35]
	v_cvt_pk_bf16_f32 v32, v36, v37
	v_mul_f32_e32 v36, 0xbfb8aa3b, v28
	v_mul_f32_e32 v37, 0xbfb8aa3b, v29
	v_exp_f32_e32 v36, v36
	v_exp_f32_e32 v37, v37
	v_cvt_pk_bf16_f32 v33, v38, v39
	v_cvt_pk_bf16_f32 v34, v40, v41
	v_cvt_pk_bf16_f32 v35, v42, v43
	global_store_dwordx4 v[44:45], v[32:35], off
	s_nop 1
	v_add_f32_e32 v32, 1.0, v36
	v_add_f32_e32 v33, 1.0, v37
	v_rcp_f32_e32 v32, v32
	v_rcp_f32_e32 v33, v33
	v_add_u32_e32 v34, 0xa0, v144
	v_mad_i64_i32 v[34:35], s[4:5], v34, s33, v[138:139]
	v_pk_mul_f32 v[28:29], v[28:29], v[32:33]
	v_mul_f32_e32 v32, 0xbfb8aa3b, v30
	v_mul_f32_e32 v33, 0xbfb8aa3b, v31
	v_exp_f32_e32 v32, v32
	v_exp_f32_e32 v33, v33
	v_pk_mul_f32 v[20:21], v[28:29], v[20:21]
	v_add_f32_e32 v28, 1.0, v32
	v_add_f32_e32 v29, 1.0, v33
	v_mul_f32_e32 v32, 0xbfb8aa3b, v24
	v_mul_f32_e32 v33, 0xbfb8aa3b, v25
	v_rcp_f32_e32 v28, v28
	v_rcp_f32_e32 v29, v29
	v_exp_f32_e32 v32, v32
	v_exp_f32_e32 v33, v33
	v_pk_mul_f32 v[28:29], v[30:31], v[28:29]
	v_add_f32_e32 v30, 1.0, v32
	v_add_f32_e32 v31, 1.0, v33
	v_mul_f32_e32 v32, 0xbfb8aa3b, v26
	v_mul_f32_e32 v33, 0xbfb8aa3b, v27
	v_exp_f32_e32 v32, v32
	v_exp_f32_e32 v33, v33
	v_rcp_f32_e32 v30, v30
	v_rcp_f32_e32 v31, v31
	v_add_f32_e32 v32, 1.0, v32
	v_add_f32_e32 v33, 1.0, v33
	v_rcp_f32_e32 v32, v32
	v_rcp_f32_e32 v33, v33
	v_pk_mul_f32 v[24:25], v[24:25], v[30:31]
	v_pk_mul_f32 v[22:23], v[28:29], v[22:23]
	v_pk_mul_f32 v[24:25], v[24:25], v[16:17]
	v_pk_mul_f32 v[16:17], v[26:27], v[32:33]
	v_lshl_add_u64 v[28:29], v[34:35], 0, v[112:113]
	v_pk_mul_f32 v[26:27], v[16:17], v[18:19]
	v_cvt_pk_bf16_f32 v16, v20, v21
	v_mul_f32_e32 v20, 0xbfb8aa3b, v12
	v_mul_f32_e32 v21, 0xbfb8aa3b, v13
	v_exp_f32_e32 v20, v20
	v_exp_f32_e32 v21, v21
	v_cvt_pk_bf16_f32 v17, v22, v23
	v_cvt_pk_bf16_f32 v18, v24, v25
	v_cvt_pk_bf16_f32 v19, v26, v27
	global_store_dwordx4 v[28:29], v[16:19], off
	s_nop 1
	v_add_f32_e32 v16, 1.0, v20
	v_add_f32_e32 v17, 1.0, v21
	v_rcp_f32_e32 v16, v16
	v_rcp_f32_e32 v17, v17
	v_add_u32_e32 v18, 0xb0, v144
	v_mad_i64_i32 v[18:19], s[4:5], v18, s33, v[138:139]
	v_pk_mul_f32 v[12:13], v[12:13], v[16:17]
	v_mul_f32_e32 v16, 0xbfb8aa3b, v14
	v_mul_f32_e32 v17, 0xbfb8aa3b, v15
	v_exp_f32_e32 v16, v16
	v_exp_f32_e32 v17, v17
	v_pk_mul_f32 v[4:5], v[12:13], v[4:5]
	s_mov_b64 s[4:5], -1
	v_add_f32_e32 v12, 1.0, v16
	v_add_f32_e32 v13, 1.0, v17
	v_mul_f32_e32 v16, 0xbfb8aa3b, v8
	v_mul_f32_e32 v17, 0xbfb8aa3b, v9
	v_rcp_f32_e32 v12, v12
	v_rcp_f32_e32 v13, v13
	v_exp_f32_e32 v16, v16
	v_exp_f32_e32 v17, v17
	v_pk_mul_f32 v[12:13], v[14:15], v[12:13]
	v_add_f32_e32 v14, 1.0, v16
	v_add_f32_e32 v15, 1.0, v17
	v_mul_f32_e32 v16, 0xbfb8aa3b, v10
	v_mul_f32_e32 v17, 0xbfb8aa3b, v11
	v_exp_f32_e32 v16, v16
	v_exp_f32_e32 v17, v17
	v_rcp_f32_e32 v14, v14
	v_rcp_f32_e32 v15, v15
	v_add_f32_e32 v16, 1.0, v16
	v_add_f32_e32 v17, 1.0, v17
	v_rcp_f32_e32 v16, v16
	v_rcp_f32_e32 v17, v17
	v_pk_mul_f32 v[8:9], v[8:9], v[14:15]
	v_pk_mul_f32 v[6:7], v[12:13], v[6:7]
	v_pk_mul_f32 v[8:9], v[8:9], v[0:1]
	v_pk_mul_f32 v[0:1], v[10:11], v[16:17]
	v_lshl_add_u64 v[12:13], v[18:19], 0, v[112:113]
	v_pk_mul_f32 v[10:11], v[0:1], v[2:3]
	v_cvt_pk_bf16_f32 v0, v4, v5
	v_cvt_pk_bf16_f32 v1, v6, v7
	v_cvt_pk_bf16_f32 v2, v8, v9
	v_cvt_pk_bf16_f32 v3, v10, v11
	global_store_dwordx4 v[12:13], v[0:3], off
	s_mov_b32 s19, 1
	s_cbranch_vccnz .LBB0_933
	s_andn2_b64 vcc, exec, s[6:7]
	s_cbranch_vccnz .LBB0_932
	s_barrier
	s_branch .LBB0_932
